# GEMM1 epilogue v tiles: g_v gain vector loaded once per unit instead of once per row group (7 fewer exposed L2 round trips)
# speedup vs baseline: 1.1031x; 1.0034x over previous
; #define PG8_STAGE(bufoff, gbase, voff) do { _Pragma("unroll") for (int _i = 0; _i < 2; ++_i) \
;         __builtin_amdgcn_global_load_lds((const unsigned*)((const char*)(gbase) + (voff)[_i]), (LAS unsigned*)(lds + (bufoff) + ldsw + _i * 8192), 16, 0, 0); } while (0)
; #define PG8_LDA(dst, b, h) do { _Pragma("unroll") for (int m = 0; m < 4; ++m) _Pragma("unroll") for (int k = 0; k < 2; ++k) dst[m][k] = *(const LAS bf16x8*)(lds + PG8_SA(b, h) + aoff + m * 2048 + k * 1024); } while (0)
; #define PG8_LDB(dst, b, h) do { _Pragma("unroll") for (int n = 0; n < 2; ++n) _Pragma("unroll") for (int k = 0; k < 2; ++k) dst[n][k] = *(const LAS bf16x8*)(lds + PG8_SB(b, h) + boff + n * 2048 + k * 1024); } while (0)
; #define PG8_WAIT_V(n) asm volatile("s_waitcnt vmcnt(" #n ")" ::: "memory")
; #define PG8_WAIT_L(n) asm volatile("s_waitcnt lgkmcnt(" #n ")" ::: "memory")
; #define PG8_BAR __builtin_amdgcn_s_barrier()
; #define PG8_SCHED __builtin_amdgcn_sched_barrier(0)
; template <class Epi>
; __device__ __forceinline__ void gemm_phase(LAS unsigned char* lds, const Gemm g, const StaticOrder& S, const Epi& E, float* smem = nullptr) {
;     ...
;             PG8_LDB(B0, 0, 0); PG8_SCHED; PG8_LDA(At, 0, 0); PG8_STAGE(PG8_SA(1, 1), a1 + hstep, voffA);
;             PG8_WAIT_L(8); PG8_BAR; PG8_WAIT_L(0); PG8_MMA(0, 0, At, B0); PG8_BAR; PG8_SCHED;
;             PG8_LDB(B1, 0, 1); PG8_STAGE(PG8_SB(0, 0), b2, voffA);
;             PG8_BAR; PG8_WAIT_L(0); PG8_MMA(0, 1, At, B1); PG8_BAR;
;             PG8_LDA(At, 0, 1); PG8_STAGE(PG8_SA(0, 0), a2, voffA);
;             PG8_BAR; PG8_WAIT_L(0); PG8_MMA(1, 0, At, B0); PG8_BAR; PG8_SCHED;
;             PG8_STAGE(PG8_SB(0, 1), b2 + hstep, voffA);
;             PG8_WAIT_V(6); PG8_BAR; PG8_MMA(1, 1, At, B1); PG8_BAR;
;             PG8_LDB(B0, 1, 0); PG8_SCHED; PG8_LDA(At, 1, 0); PG8_STAGE(PG8_SA(0, 1), a2 + hstep, voffA);
;             PG8_WAIT_L(8); PG8_BAR; PG8_WAIT_L(0); PG8_MMA(0, 0, At, B0); PG8_BAR; PG8_SCHED;
;             PG8_LDB(B1, 1, 1); PG8_STAGE(PG8_SB(1, 0), b3, voffA);
;             PG8_BAR; PG8_WAIT_L(0); PG8_MMA(0, 1, At, B1); PG8_BAR;
;             PG8_LDA(At, 1, 1); PG8_STAGE(PG8_SA(1, 0), a3, voffA);
;             PG8_BAR; PG8_WAIT_L(0); PG8_MMA(1, 0, At, B0); PG8_BAR; PG8_SCHED;
;             PG8_STAGE(PG8_SB(1, 1), b3 + hstep, voffA);
;             PG8_WAIT_V(6); PG8_BAR; PG8_MMA(1, 1, At, B1); PG8_BAR;
.LBB0_212:
	ds_read_b128 v[128:131], v185
	ds_read_b128 v[132:135], v185 offset:1024
	ds_read_b128 v[152:155], v185 offset:2048
	ds_read_b128 v[156:159], v185 offset:3072
	s_add_u32 s8, s6, 0xfffc0080
	s_addc_u32 s9, s7, -1
	s_cmp_eq_u32 s80, 12
	s_cselect_b32 s11, s1, s9
	s_cselect_b32 s10, s5, s8
	s_cselect_b32 s9, s61, s75
	s_cselect_b32 s8, s64, s73
	v_lshl_add_u64 v[180:181], s[6:7], 0, v[144:145]
	s_add_i32 m0, s86, 0xc000
	ds_read_b128 v[160:163], v186
	ds_read_b128 v[164:167], v186 offset:1024
	ds_read_b128 v[168:171], v186 offset:2048
	ds_read_b128 v[172:175], v186 offset:3072
	ds_read_b128 v[176:179], v186 offset:4096
	ds_read_b128 v[190:193], v186 offset:5120
	ds_read_b128 v[194:197], v186 offset:6144
	ds_read_b128 v[198:201], v186 offset:7168
	global_load_lds_dwordx4 v[180:181], off
	v_lshl_add_u64 v[180:181], s[6:7], 0, v[146:147]
	s_add_i32 m0, s86, 0xe000
	s_nop 0
	global_load_lds_dwordx4 v[180:181], off
	s_waitcnt lgkmcnt(8)
	s_barrier
	s_waitcnt lgkmcnt(0)
	s_waitcnt lgkmcnt(0)
	v_mfma_f32_16x16x32_bf16 v[124:127], v[128:131], v[160:163], v[124:127]
	v_mfma_f32_16x16x32_bf16 v[120:123], v[152:155], v[160:163], v[120:123]
	v_mfma_f32_16x16x32_bf16 v[108:111], v[128:131], v[168:171], v[108:111]
	v_mfma_f32_16x16x32_bf16 v[104:107], v[152:155], v[168:171], v[104:107]
	v_mfma_f32_16x16x32_bf16 v[92:95], v[128:131], v[176:179], v[92:95]
	v_mfma_f32_16x16x32_bf16 v[88:91], v[152:155], v[176:179], v[88:91]
	v_mfma_f32_16x16x32_bf16 v[76:79], v[128:131], v[194:197], v[76:79]
	v_mfma_f32_16x16x32_bf16 v[72:75], v[152:155], v[194:197], v[72:75]
	v_mfma_f32_16x16x32_bf16 v[124:127], v[132:135], v[164:167], v[124:127]
	v_mfma_f32_16x16x32_bf16 v[120:123], v[156:159], v[164:167], v[120:123]
	v_mfma_f32_16x16x32_bf16 v[108:111], v[132:135], v[172:175], v[108:111]
	v_mfma_f32_16x16x32_bf16 v[104:107], v[156:159], v[172:175], v[104:107]
	v_mfma_f32_16x16x32_bf16 v[92:95], v[132:135], v[190:193], v[92:95]
	v_mfma_f32_16x16x32_bf16 v[88:91], v[156:159], v[190:193], v[88:91]
	v_mfma_f32_16x16x32_bf16 v[76:79], v[132:135], v[198:201], v[76:79]
	v_mfma_f32_16x16x32_bf16 v[72:75], v[156:159], v[198:201], v[72:75]
	s_barrier
	s_add_i32 s81, s84, s85
	v_lshl_add_u64 v[180:181], s[8:9], 0, v[136:137]
	s_mov_b32 m0, s81
	ds_read_b128 v[202:205], v187
	ds_read_b128 v[206:209], v187 offset:1024
	ds_read_b128 v[210:213], v187 offset:2048
	ds_read_b128 v[214:217], v187 offset:3072
	global_load_lds_dwordx4 v[180:181], off
	v_lshl_add_u64 v[218:219], s[8:9], 0, v[138:139]
	s_add_i32 m0, s81, 0x2000
	s_nop 0
	global_load_lds_dwordx4 v[218:219], off
	s_barrier
	s_waitcnt lgkmcnt(0)
	s_waitcnt lgkmcnt(0)
	v_mfma_f32_16x16x32_bf16 v[116:119], v[202:205], v[160:163], v[116:119]
	v_mfma_f32_16x16x32_bf16 v[112:115], v[210:213], v[160:163], v[112:115]
	v_mfma_f32_16x16x32_bf16 v[100:103], v[202:205], v[168:171], v[100:103]
	v_mfma_f32_16x16x32_bf16 v[96:99], v[210:213], v[168:171], v[96:99]
	v_mfma_f32_16x16x32_bf16 v[84:87], v[202:205], v[176:179], v[84:87]
	v_mfma_f32_16x16x32_bf16 v[80:83], v[210:213], v[176:179], v[80:83]
	v_mfma_f32_16x16x32_bf16 v[68:71], v[202:205], v[194:197], v[68:71]
	v_mfma_f32_16x16x32_bf16 v[64:67], v[210:213], v[194:197], v[64:67]
	v_mfma_f32_16x16x32_bf16 v[116:119], v[206:209], v[164:167], v[116:119]
	v_mfma_f32_16x16x32_bf16 v[112:115], v[214:217], v[164:167], v[112:115]
	v_mfma_f32_16x16x32_bf16 v[100:103], v[206:209], v[172:175], v[100:103]
	v_mfma_f32_16x16x32_bf16 v[96:99], v[214:217], v[172:175], v[96:99]
	v_mfma_f32_16x16x32_bf16 v[84:87], v[206:209], v[190:193], v[84:87]
	v_mfma_f32_16x16x32_bf16 v[80:83], v[214:217], v[190:193], v[80:83]
	v_mfma_f32_16x16x32_bf16 v[68:71], v[206:209], v[198:201], v[68:71]
	v_mfma_f32_16x16x32_bf16 v[64:67], v[214:217], v[198:201], v[64:67]
	s_mov_b32 m0, s86
	v_lshl_add_u64 v[220:221], s[10:11], 0, v[136:137]
	s_barrier
	ds_read_b128 v[160:163], v186 offset:16384
	ds_read_b128 v[164:167], v186 offset:17408
	ds_read_b128 v[168:171], v186 offset:18432
	ds_read_b128 v[172:175], v186 offset:19456
	ds_read_b128 v[176:179], v186 offset:20480
	ds_read_b128 v[190:193], v186 offset:21504
	ds_read_b128 v[194:197], v186 offset:22528
	ds_read_b128 v[198:201], v186 offset:23552
	global_load_lds_dwordx4 v[220:221], off
	v_lshl_add_u64 v[222:223], s[10:11], 0, v[138:139]
	s_mov_b32 m0, s87
	s_nop 0
	global_load_lds_dwordx4 v[222:223], off
	s_barrier
	s_waitcnt lgkmcnt(0)
	s_waitcnt lgkmcnt(0)
	v_mfma_f32_16x16x32_bf16 v[60:63], v[128:131], v[160:163], v[60:63]
	v_mfma_f32_16x16x32_bf16 v[56:59], v[152:155], v[160:163], v[56:59]
	v_mfma_f32_16x16x32_bf16 v[44:47], v[128:131], v[168:171], v[44:47]
	v_mfma_f32_16x16x32_bf16 v[40:43], v[152:155], v[168:171], v[40:43]
	v_mfma_f32_16x16x32_bf16 v[28:31], v[128:131], v[176:179], v[28:31]
	v_mfma_f32_16x16x32_bf16 v[24:27], v[152:155], v[176:179], v[24:27]
	v_mfma_f32_16x16x32_bf16 v[12:15], v[128:131], v[194:197], v[12:15]
	v_mfma_f32_16x16x32_bf16 v[8:11], v[152:155], v[194:197], v[8:11]
	v_mfma_f32_16x16x32_bf16 v[60:63], v[132:135], v[164:167], v[60:63]
	v_mfma_f32_16x16x32_bf16 v[56:59], v[156:159], v[164:167], v[56:59]
	v_mfma_f32_16x16x32_bf16 v[44:47], v[132:135], v[172:175], v[44:47]
	v_mfma_f32_16x16x32_bf16 v[40:43], v[156:159], v[172:175], v[40:43]
	v_mfma_f32_16x16x32_bf16 v[28:31], v[132:135], v[190:193], v[28:31]
	v_mfma_f32_16x16x32_bf16 v[24:27], v[156:159], v[190:193], v[24:27]
	v_mfma_f32_16x16x32_bf16 v[12:15], v[132:135], v[198:201], v[12:15]
	v_mfma_f32_16x16x32_bf16 v[8:11], v[156:159], v[198:201], v[8:11]
	s_barrier
; #define PG8_STAGE(bufoff, gbase, voff) do { _Pragma("unroll") for (int _i = 0; _i < 2; ++_i) \
;         __builtin_amdgcn_global_load_lds((const unsigned*)((const char*)(gbase) + (voff)[_i]), (LAS unsigned*)(lds + (bufoff) + ldsw + _i * 8192), 16, 0, 0); } while (0)
; #define PG8_LDA(dst, b, h) do { _Pragma("unroll") for (int m = 0; m < 4; ++m) _Pragma("unroll") for (int k = 0; k < 2; ++k) dst[m][k] = *(const LAS bf16x8*)(lds + PG8_SA(b, h) + aoff + m * 2048 + k * 1024); } while (0)
; #define PG8_LDB(dst, b, h) do { _Pragma("unroll") for (int n = 0; n < 2; ++n) _Pragma("unroll") for (int k = 0; k < 2; ++k) dst[n][k] = *(const LAS bf16x8*)(lds + PG8_SB(b, h) + boff + n * 2048 + k * 1024); } while (0)
; #define PG8_MMA(ai, bj, At, Bt) do { __builtin_amdgcn_s_setprio(1); _Pragma("unroll") for (int m = 0; m < 4; ++m) _Pragma("unroll") for (int n = 0; n < 2; ++n) _Pragma("unroll") for (int k = 0; k < 2; ++k) \
;         acc[ai][bj][m][n] = __builtin_amdgcn_mfma_f32_16x16x32_bf16(Bt[n][k], At[m][k], acc[ai][bj][m][n], 0, 0, 0); __builtin_amdgcn_s_setprio(0); } while (0)
; #define PG8_WAIT_V(n) asm volatile("s_waitcnt vmcnt(" #n ")" ::: "memory")
; #define PG8_WAIT_L(n) asm volatile("s_waitcnt lgkmcnt(" #n ")" ::: "memory")
; #define PG8_BAR __builtin_amdgcn_s_barrier()
; #define PG8_SCHED __builtin_amdgcn_sched_barrier(0)
; template <class Epi>
; __device__ __forceinline__ void gemm_phase(LAS unsigned char* lds, const Gemm g, const StaticOrder& S, const Epi& E, float* smem = nullptr) {
;     ...
;             PG8_STAGE(PG8_SB(0, 1), b2 + hstep, voffA);
;             PG8_WAIT_V(6); PG8_BAR; PG8_MMA(1, 1, At, B1); PG8_BAR;
;             PG8_LDB(B0, 1, 0); PG8_SCHED; PG8_LDA(At, 1, 0); PG8_STAGE(PG8_SA(0, 1), a2 + hstep, voffA);
;             PG8_WAIT_L(8); PG8_BAR; PG8_WAIT_L(0); PG8_MMA(0, 0, At, B0); PG8_BAR; PG8_SCHED;
;             PG8_LDB(B1, 1, 1); PG8_STAGE(PG8_SB(1, 0), b3, voffA);
;             PG8_BAR; PG8_WAIT_L(0); PG8_MMA(0, 1, At, B1); PG8_BAR;
;             PG8_LDA(At, 1, 1); PG8_STAGE(PG8_SA(1, 0), a3, voffA);
;             PG8_BAR; PG8_WAIT_L(0); PG8_MMA(1, 0, At, B0); PG8_BAR; PG8_SCHED;
	s_add_u32 s82, s8, 0x40000
	s_addc_u32 s83, s9, 0
	s_add_i32 s81, s33, s85
	v_lshl_add_u64 v[128:129], s[82:83], 0, v[136:137]
	s_mov_b32 m0, s81
	s_nop 0
	global_load_lds_dwordx4 v[128:129], off
	v_lshl_add_u64 v[128:129], s[82:83], 0, v[138:139]
	s_add_i32 m0, s81, 0x2000
	s_nop 0
	global_load_lds_dwordx4 v[128:129], off
	s_waitcnt vmcnt(6)
	s_barrier
	v_mfma_f32_16x16x32_bf16 v[52:55], v[202:205], v[160:163], v[52:55]
	v_mfma_f32_16x16x32_bf16 v[48:51], v[210:213], v[160:163], v[48:51]
	v_mfma_f32_16x16x32_bf16 v[36:39], v[202:205], v[168:171], v[36:39]
	v_mfma_f32_16x16x32_bf16 v[32:35], v[210:213], v[168:171], v[32:35]
	v_mfma_f32_16x16x32_bf16 v[20:23], v[202:205], v[176:179], v[20:23]
	v_mfma_f32_16x16x32_bf16 v[16:19], v[210:213], v[176:179], v[16:19]
	v_mfma_f32_16x16x32_bf16 v[4:7], v[202:205], v[194:197], v[4:7]
	v_mfma_f32_16x16x32_bf16 v[0:3], v[210:213], v[194:197], v[0:3]
	v_mfma_f32_16x16x32_bf16 v[52:55], v[206:209], v[164:167], v[52:55]
	v_mfma_f32_16x16x32_bf16 v[48:51], v[214:217], v[164:167], v[48:51]
	v_mfma_f32_16x16x32_bf16 v[36:39], v[206:209], v[172:175], v[36:39]
	v_mfma_f32_16x16x32_bf16 v[32:35], v[214:217], v[172:175], v[32:35]
	v_mfma_f32_16x16x32_bf16 v[20:23], v[206:209], v[190:193], v[20:23]
	v_mfma_f32_16x16x32_bf16 v[16:19], v[214:217], v[190:193], v[16:19]
	v_mfma_f32_16x16x32_bf16 v[4:7], v[206:209], v[198:201], v[4:7]
	v_mfma_f32_16x16x32_bf16 v[0:3], v[214:217], v[198:201], v[0:3]
	s_add_i32 s81, 16, 0x18000
	v_add_u32_e32 v140, s81, v182
	s_barrier
	ds_read_b128 v[128:131], v140
	ds_read_b128 v[132:135], v140 offset:1024
	ds_read_b128 v[152:155], v140 offset:2048
	ds_read_b128 v[156:159], v140 offset:3072
	s_add_u32 s10, s10, 0x40000
	s_addc_u32 s11, s11, 0
	s_mov_b32 m0, s88
	v_lshl_add_u64 v[202:203], s[10:11], 0, v[136:137]
	ds_read_b128 v[160:163], v186 offset:32768
	ds_read_b128 v[164:167], v186 offset:33792
	ds_read_b128 v[168:171], v186 offset:34816
	ds_read_b128 v[172:175], v186 offset:35840
	ds_read_b128 v[176:179], v186 offset:36864
	ds_read_b128 v[190:193], v186 offset:37888
	ds_read_b128 v[194:197], v186 offset:38912
	ds_read_b128 v[198:201], v186 offset:39936
	global_load_lds_dwordx4 v[202:203], off
	v_lshl_add_u64 v[202:203], s[10:11], 0, v[138:139]
	s_mov_b32 m0, s89
	s_nop 0
	global_load_lds_dwordx4 v[202:203], off
	s_waitcnt lgkmcnt(8)
	s_barrier
	s_waitcnt lgkmcnt(0)
	s_waitcnt lgkmcnt(0)
	v_mfma_f32_16x16x32_bf16 v[124:127], v[128:131], v[160:163], v[124:127]
	v_mfma_f32_16x16x32_bf16 v[120:123], v[152:155], v[160:163], v[120:123]
	v_mfma_f32_16x16x32_bf16 v[108:111], v[128:131], v[168:171], v[108:111]
	v_mfma_f32_16x16x32_bf16 v[104:107], v[152:155], v[168:171], v[104:107]
	v_mfma_f32_16x16x32_bf16 v[92:95], v[128:131], v[176:179], v[92:95]
	v_mfma_f32_16x16x32_bf16 v[88:91], v[152:155], v[176:179], v[88:91]
	v_mfma_f32_16x16x32_bf16 v[76:79], v[128:131], v[194:197], v[76:79]
	v_mfma_f32_16x16x32_bf16 v[72:75], v[152:155], v[194:197], v[72:75]
	v_mfma_f32_16x16x32_bf16 v[124:127], v[132:135], v[164:167], v[124:127]
	v_mfma_f32_16x16x32_bf16 v[120:123], v[156:159], v[164:167], v[120:123]
	v_mfma_f32_16x16x32_bf16 v[108:111], v[132:135], v[172:175], v[108:111]
	v_mfma_f32_16x16x32_bf16 v[104:107], v[156:159], v[172:175], v[104:107]
	v_mfma_f32_16x16x32_bf16 v[92:95], v[132:135], v[190:193], v[92:95]
	v_mfma_f32_16x16x32_bf16 v[88:91], v[156:159], v[190:193], v[88:91]
	v_mfma_f32_16x16x32_bf16 v[76:79], v[132:135], v[198:201], v[76:79]
	v_mfma_f32_16x16x32_bf16 v[72:75], v[156:159], v[198:201], v[72:75]
	s_barrier
	s_add_i32 s10, 16, 0x1c000
	s_add_i32 s11, s81, s85
	v_add_u32_e32 v140, s10, v182
	v_lshl_add_u64 v[180:181], v[180:181], 0, s[52:53]
	s_mov_b32 m0, s11
	ds_read_b128 v[202:205], v140
	ds_read_b128 v[206:209], v140 offset:1024
	ds_read_b128 v[210:213], v140 offset:2048
	ds_read_b128 v[214:217], v140 offset:3072
	global_load_lds_dwordx4 v[180:181], off
	v_lshl_add_u64 v[180:181], v[218:219], 0, s[52:53]
	s_add_i32 m0, s11, 0x2000
	s_nop 0
	global_load_lds_dwordx4 v[180:181], off
	s_barrier
	s_waitcnt lgkmcnt(0)
	s_waitcnt lgkmcnt(0)
	v_mfma_f32_16x16x32_bf16 v[116:119], v[202:205], v[160:163], v[116:119]
	v_mfma_f32_16x16x32_bf16 v[112:115], v[210:213], v[160:163], v[112:115]
	v_mfma_f32_16x16x32_bf16 v[100:103], v[202:205], v[168:171], v[100:103]
	v_mfma_f32_16x16x32_bf16 v[96:99], v[210:213], v[168:171], v[96:99]
	v_mfma_f32_16x16x32_bf16 v[84:87], v[202:205], v[176:179], v[84:87]
	v_mfma_f32_16x16x32_bf16 v[80:83], v[210:213], v[176:179], v[80:83]
	v_mfma_f32_16x16x32_bf16 v[68:71], v[202:205], v[194:197], v[68:71]
	v_mfma_f32_16x16x32_bf16 v[64:67], v[210:213], v[194:197], v[64:67]
	v_mfma_f32_16x16x32_bf16 v[116:119], v[206:209], v[164:167], v[116:119]
	v_mfma_f32_16x16x32_bf16 v[112:115], v[214:217], v[164:167], v[112:115]
	v_mfma_f32_16x16x32_bf16 v[100:103], v[206:209], v[172:175], v[100:103]
	v_mfma_f32_16x16x32_bf16 v[96:99], v[214:217], v[172:175], v[96:99]
	v_mfma_f32_16x16x32_bf16 v[84:87], v[206:209], v[190:193], v[84:87]
	v_mfma_f32_16x16x32_bf16 v[80:83], v[214:217], v[190:193], v[80:83]
	v_mfma_f32_16x16x32_bf16 v[68:71], v[206:209], v[198:201], v[68:71]
	v_mfma_f32_16x16x32_bf16 v[64:67], v[214:217], v[198:201], v[64:67]
	s_mov_b32 m0, s96
	v_lshl_add_u64 v[180:181], v[220:221], 0, s[52:53]
	s_barrier
; #define PG8_WAIT_V(n) asm volatile("s_waitcnt vmcnt(" #n ")" ::: "memory")
;     __device__ __forceinline__ void row(const f32x4 (&a)[2][2], int row, int pn, int wc, int fq) const {
;         if (pn < 2 || pn == 4 || pn == 5) {
;             bf16_t* dst = (pn < 2 ? pU : pBG) + (size_t)row * 512 + (pn & 1) * 256 + wc * 32 + 8 * fq;
; #pragma unroll
;             for (int bj = 0; bj < 2; ++bj) { f32x4 v0 = a[bj][0], v1 = a[bj][1];
;                 if (pn < 2) {
; #pragma unroll
;                     for (int j = 0; j < 4; ++j) { v0[j] = gelu_tanh(v0[j]); v1[j] = gelu_tanh(v1[j]); } }
;                 st_bf16x8(dst + bj * HALF, v0, v1); }
;         } else if (pn < 4) {
;             const int head = (pn - 2) * 4 + wc;
;             f32x4 g[2][2]; float ss = 0.f;
; #pragma unroll
;             for (int bj = 0; bj < 2; ++bj)
; #pragma unroll
;                 for (int n = 0; n < 2; ++n)
; #pragma unroll
;                     for (int j = 0; j < 4; ++j) { const float t = gelu_tanh(a[bj][n][j]); g[bj][n][j] = t; ss += t * t; }
;             ss += __shfl_xor(ss, 16); ss += __shfl_xor(ss, 32);
;             const float rs = rsqrtf(ss * (1.f / 64.f) + EPS);
; #pragma unroll
;             for (int bj = 0; bj < 2; ++bj) { const int d = head * 64 + bj * 32 + 8 * fq;
;                 const f32x4 v0 = g[bj][0] * rs * *(const f32x4*)(g_v + d), v1 = g[bj][1] * rs * *(const f32x4*)(g_v + d + 4);
;                 st_bf16x8(pV + (size_t)row * 512 + d, v0, v1);
;                 if (row >= NP && row < NTOK) { float* o = out + O_VS + (size_t)(row - NP) * 512 + d; *(f32x4*)o = v0; *(f32x4*)(o + 4) = v1; } }
;         } else {
;             const int c = (pn - 6) * 128 + wc * 32 + 8 * fq;
;             const f32x4 z0 = a[0][0] * a[1][0], z1 = a[0][1] * a[1][1];
;             st_bf16x8(pZ + (size_t)row * 512 + c, z0, z1);
;             float* o = nullptr;
; template <class Epi>
; __device__ __forceinline__ void gemm_phase(LAS unsigned char* lds, const Gemm g, const StaticOrder& S, const Epi& E, float* smem = nullptr) {
;     ...
;             PG8_LDA(At, 1, 1); PG8_STAGE(PG8_SA(1, 0), a3, voffA);
;             PG8_BAR; PG8_WAIT_L(0); PG8_MMA(1, 0, At, B0); PG8_BAR; PG8_SCHED;
;             PG8_STAGE(PG8_SB(1, 1), b3 + hstep, voffA);
;             PG8_WAIT_V(6); PG8_BAR; PG8_MMA(1, 1, At, B1); PG8_BAR;
;         }
;         if constexpr (!Epi::AFTER_DRAIN) E(acc, cur, wr, wc, fr, fq);
	ds_read_b128 v[160:163], v186 offset:49152
	ds_read_b128 v[164:167], v186 offset:50176
	ds_read_b128 v[168:171], v186 offset:51200
	ds_read_b128 v[172:175], v186 offset:52224
	ds_read_b128 v[176:179], v186 offset:53248
	ds_read_b128 v[190:193], v186 offset:54272
	ds_read_b128 v[194:197], v186 offset:55296
	ds_read_b128 v[198:201], v186 offset:56320
	global_load_lds_dwordx4 v[180:181], off
	v_lshl_add_u64 v[180:181], v[222:223], 0, s[52:53]
	s_mov_b32 m0, s97
	s_nop 0
	global_load_lds_dwordx4 v[180:181], off
	s_barrier
	s_waitcnt lgkmcnt(0)
	s_waitcnt lgkmcnt(0)
	v_mfma_f32_16x16x32_bf16 v[60:63], v[128:131], v[160:163], v[60:63]
	v_mfma_f32_16x16x32_bf16 v[56:59], v[152:155], v[160:163], v[56:59]
	v_mfma_f32_16x16x32_bf16 v[44:47], v[128:131], v[168:171], v[44:47]
	v_mfma_f32_16x16x32_bf16 v[40:43], v[152:155], v[168:171], v[40:43]
	v_mfma_f32_16x16x32_bf16 v[28:31], v[128:131], v[176:179], v[28:31]
	v_mfma_f32_16x16x32_bf16 v[24:27], v[152:155], v[176:179], v[24:27]
	v_mfma_f32_16x16x32_bf16 v[12:15], v[128:131], v[194:197], v[12:15]
	v_mfma_f32_16x16x32_bf16 v[8:11], v[152:155], v[194:197], v[8:11]
	v_mfma_f32_16x16x32_bf16 v[60:63], v[132:135], v[164:167], v[60:63]
	v_mfma_f32_16x16x32_bf16 v[56:59], v[156:159], v[164:167], v[56:59]
	v_mfma_f32_16x16x32_bf16 v[44:47], v[132:135], v[172:175], v[44:47]
	v_mfma_f32_16x16x32_bf16 v[40:43], v[156:159], v[172:175], v[40:43]
	v_mfma_f32_16x16x32_bf16 v[28:31], v[132:135], v[190:193], v[28:31]
	v_mfma_f32_16x16x32_bf16 v[24:27], v[156:159], v[190:193], v[24:27]
	v_mfma_f32_16x16x32_bf16 v[12:15], v[132:135], v[198:201], v[12:15]
	v_mfma_f32_16x16x32_bf16 v[8:11], v[156:159], v[198:201], v[8:11]
	s_barrier
	s_add_u32 s8, s8, 0x40080
	s_addc_u32 s9, s9, 0
	s_add_i32 s10, s10, s85
	v_lshl_add_u64 v[128:129], s[8:9], 0, v[136:137]
	s_mov_b32 m0, s10
	s_nop 0
	global_load_lds_dwordx4 v[128:129], off
	v_lshl_add_u64 v[128:129], s[8:9], 0, v[138:139]
	s_add_i32 m0, s10, 0x2000
	s_nop 0
	global_load_lds_dwordx4 v[128:129], off
	s_waitcnt vmcnt(6)
	s_barrier
	v_mfma_f32_16x16x32_bf16 v[52:55], v[202:205], v[160:163], v[52:55]
	v_mfma_f32_16x16x32_bf16 v[48:51], v[210:213], v[160:163], v[48:51]
	v_mfma_f32_16x16x32_bf16 v[36:39], v[202:205], v[168:171], v[36:39]
	v_mfma_f32_16x16x32_bf16 v[32:35], v[210:213], v[168:171], v[32:35]
	v_mfma_f32_16x16x32_bf16 v[20:23], v[202:205], v[176:179], v[20:23]
	v_mfma_f32_16x16x32_bf16 v[16:19], v[210:213], v[176:179], v[16:19]
	v_mfma_f32_16x16x32_bf16 v[4:7], v[202:205], v[194:197], v[4:7]
	v_mfma_f32_16x16x32_bf16 v[0:3], v[210:213], v[194:197], v[0:3]
	v_mfma_f32_16x16x32_bf16 v[52:55], v[206:209], v[164:167], v[52:55]
	v_mfma_f32_16x16x32_bf16 v[48:51], v[214:217], v[164:167], v[48:51]
	v_mfma_f32_16x16x32_bf16 v[36:39], v[206:209], v[172:175], v[36:39]
	v_mfma_f32_16x16x32_bf16 v[32:35], v[214:217], v[172:175], v[32:35]
	v_mfma_f32_16x16x32_bf16 v[20:23], v[206:209], v[190:193], v[20:23]
	v_mfma_f32_16x16x32_bf16 v[16:19], v[214:217], v[190:193], v[16:19]
	v_mfma_f32_16x16x32_bf16 v[4:7], v[206:209], v[198:201], v[4:7]
	v_mfma_f32_16x16x32_bf16 v[0:3], v[214:217], v[198:201], v[0:3]
	s_add_i32 s80, s80, 2
	s_add_u32 s6, s6, 0x100
	s_addc_u32 s7, s7, 0
	s_add_u32 s73, s73, 0x100
	s_addc_u32 s75, s75, 0
	s_cmp_gt_u32 s80, 13
	s_barrier
	s_cbranch_scc0 .LBB0_212
	s_lshl_b32 s73, s4, 8
	s_add_i32 s73, s73, s90
	s_cmp_lt_i32 s0, 2
	s_cselect_b64 s[80:81], -1, 0
	s_cmp_gt_i32 s0, 1
	s_cselect_b64 s[4:5], -1, 0
	s_and_b32 s1, s0, -2
	s_cmp_lg_u32 s1, 4
	s_cselect_b64 s[6:7], -1, 0
	s_and_b64 s[6:7], s[4:5], s[6:7]
	s_cmp_gt_u32 s0, 3
	s_cselect_b64 s[82:83], -1, 0
	s_lshl_b32 s4, s0, 8
	s_and_b32 s75, s73, 0xffffff80
	v_lshl_add_u32 v154, s0, 7, v183
	v_add_u32_e32 v140, s4, v184
	s_cmpk_eq_i32 s75, 0x4000
	v_or_b32_e32 v156, s73, v143
	v_ashrrev_i32_e32 v155, 31, v154
	v_or_b32_e32 v152, 32, v140
	v_mov_b32_e32 v153, v141
	s_mov_b64 s[0:1], -1
	s_cselect_b64 s[10:11], -1, 0
	s_andn2_b64 s[98:99], s[6:7], s[82:83]
	s_mov_b64 s[100:101], exec
	s_and_b64 exec, exec, s[98:99]
	v_lshl_add_u64 v[220:221], v[140:141], 2, s[18:19]
	global_load_dwordx4 v[204:207], v[220:221], off
	global_load_dwordx4 v[208:211], v[220:221], off offset:16
	global_load_dwordx4 v[212:215], v[220:221], off offset:128
	global_load_dwordx4 v[216:219], v[220:221], off offset:144
	s_mov_b64 exec, s[100:101]
	s_and_b64 vcc, exec, s[6:7]
	s_cbranch_vccz .LBB0_224
	s_and_b64 vcc, exec, s[82:83]
	s_cbranch_vccz .LBB0_218
	v_ashrrev_i32_e32 v157, 31, v156
	v_lshlrev_b64 v[158:159], 10, v[156:157]
	s_cmpk_lt_u32 s73, 0x4080
	v_lshl_add_u64 v[158:159], s[50:51], 0, v[158:159]
	v_cmp_lt_i32_e32 vcc, s12, v156
	s_cselect_b64 s[0:1], -1, 0
	v_pk_mul_f32 v[130:131], v[126:127], v[118:119]
	v_pk_mul_f32 v[128:129], v[124:125], v[116:117]
	v_pk_mul_f32 v[134:135], v[122:123], v[114:115]
	v_pk_mul_f32 v[132:133], v[120:121], v[112:113]
	v_lshl_add_u64 v[162:163], v[154:155], 1, v[158:159]
	s_and_b64 s[8:9], s[0:1], vcc
	v_cvt_pk_bf16_f32 v158, v128, v129
	v_cvt_pk_bf16_f32 v159, v130, v131
	v_cvt_pk_bf16_f32 v160, v132, v133
	v_cvt_pk_bf16_f32 v161, v134, v135
	global_store_dwordx4 v[162:163], v[158:161], off
	s_and_saveexec_b64 s[0:1], s[8:9]
	s_cbranch_execz .LBB0_217
	v_lshl_add_u32 v158, v156, 1, v189
	v_mov_b32_e32 v159, v141
	v_lshlrev_b64 v[158:159], 11, v[158:159]
	v_lshl_add_u64 v[158:159], s[66:67], 0, v[158:159]
	v_lshl_add_u64 v[158:159], v[154:155], 2, v[158:159]
	global_store_dwordx4 v[158:159], v[128:131], off
	global_store_dwordx4 v[158:159], v[132:135], off offset:16

; __device__ __forceinline__ float gelu_tanh(float x) { const float u = 1.5957691216f * (x + 0.044715f * x * x * x); return x * __builtin_amdgcn_rcpf(1.f + __expf(-u)); }
; __device__ __forceinline__ void st_bf16x8(bf16_t* p, const f32x4 a, const f32x4 b) { uint4 o; o.x = cvt_pk_bf16(a[0], a[1]); o.y = cvt_pk_bf16(a[2], a[3]); o.z = cvt_pk_bf16(b[0], b[1]); o.w = cvt_pk_bf16(b[2], b[3]); *(uint4*)p = o; }
;     __device__ __forceinline__ void row(const f32x4 (&a)[2][2], int row, int pn, int wc, int fq) const {
;     ...
;             const int head = (pn - 2) * 4 + wc;
;             f32x4 g[2][2]; float ss = 0.f;
; #pragma unroll
;             for (int bj = 0; bj < 2; ++bj)
; #pragma unroll
;                 for (int n = 0; n < 2; ++n)
; #pragma unroll
;                     for (int j = 0; j < 4; ++j) { const float t = gelu_tanh(a[bj][n][j]); g[bj][n][j] = t; ss += t * t; }
;             ss += __shfl_xor(ss, 16); ss += __shfl_xor(ss, 32);
;             const float rs = rsqrtf(ss * (1.f / 64.f) + EPS);
; #pragma unroll
;             for (int bj = 0; bj < 2; ++bj) { const int d = head * 64 + bj * 32 + 8 * fq;
;                 const f32x4 v0 = g[bj][0] * rs * *(const f32x4*)(g_v + d), v1 = g[bj][1] * rs * *(const f32x4*)(g_v + d + 4);
;                 st_bf16x8(pV + (size_t)row * 512 + d, v0, v1);
;                 if (row >= NP && row < NTOK) { float* o = out + O_VS + (size_t)(row - NP) * 512 + d; *(f32x4*)o = v0; *(f32x4*)(o + 4) = v1; } }
.LBB0_218:
	s_andn2_b64 vcc, exec, s[0:1]
	s_cbranch_vccnz .LBB0_223
	v_mov_b32_e32 v190, 0x3d372713
	v_mov_b32_e32 v192, 0xbfcc422a
	v_mov_b32_e32 v194, 0x3fb8aa3b
	v_pk_mul_f32 v[128:129], v[124:125], v[190:191] op_sel_hi:[1,0]
	v_pk_mul_f32 v[132:133], v[126:127], v[190:191] op_sel_hi:[1,0]
	v_pk_mul_f32 v[158:159], v[120:121], v[190:191] op_sel_hi:[1,0]
	v_pk_mul_f32 v[160:161], v[122:123], v[190:191] op_sel_hi:[1,0]
	v_pk_mul_f32 v[162:163], v[116:117], v[190:191] op_sel_hi:[1,0]
	v_pk_mul_f32 v[164:165], v[118:119], v[190:191] op_sel_hi:[1,0]
	v_pk_mul_f32 v[166:167], v[112:113], v[190:191] op_sel_hi:[1,0]
	v_pk_mul_f32 v[168:169], v[114:115], v[190:191] op_sel_hi:[1,0]
	v_pk_mul_f32 v[128:129], v[124:125], v[128:129]
	v_pk_mul_f32 v[132:133], v[126:127], v[132:133]
	v_pk_mul_f32 v[158:159], v[120:121], v[158:159]
	v_pk_mul_f32 v[160:161], v[122:123], v[160:161]
	v_pk_mul_f32 v[162:163], v[116:117], v[162:163]
	v_pk_mul_f32 v[164:165], v[118:119], v[164:165]
	v_pk_mul_f32 v[166:167], v[112:113], v[166:167]
	v_pk_mul_f32 v[168:169], v[114:115], v[168:169]
	v_pk_fma_f32 v[128:129], v[124:125], v[128:129], v[124:125]
	v_pk_fma_f32 v[132:133], v[126:127], v[132:133], v[126:127]
	v_pk_fma_f32 v[158:159], v[120:121], v[158:159], v[120:121]
	v_pk_fma_f32 v[160:161], v[122:123], v[160:161], v[122:123]
	v_pk_fma_f32 v[162:163], v[116:117], v[162:163], v[116:117]
	v_pk_fma_f32 v[164:165], v[118:119], v[164:165], v[118:119]
	v_pk_fma_f32 v[166:167], v[112:113], v[166:167], v[112:113]
	v_pk_fma_f32 v[168:169], v[114:115], v[168:169], v[114:115]
	v_pk_mul_f32 v[128:129], v[128:129], v[192:193] op_sel_hi:[1,0]
	v_pk_mul_f32 v[132:133], v[132:133], v[192:193] op_sel_hi:[1,0]
	v_pk_mul_f32 v[158:159], v[158:159], v[192:193] op_sel_hi:[1,0]
	v_pk_mul_f32 v[160:161], v[160:161], v[192:193] op_sel_hi:[1,0]
	v_pk_mul_f32 v[162:163], v[162:163], v[192:193] op_sel_hi:[1,0]
	v_pk_mul_f32 v[164:165], v[164:165], v[192:193] op_sel_hi:[1,0]
	v_pk_mul_f32 v[166:167], v[166:167], v[192:193] op_sel_hi:[1,0]
	v_pk_mul_f32 v[168:169], v[168:169], v[192:193] op_sel_hi:[1,0]
	v_pk_mul_f32 v[128:129], v[128:129], v[194:195] op_sel_hi:[1,0]
	v_pk_mul_f32 v[132:133], v[132:133], v[194:195] op_sel_hi:[1,0]
	v_pk_mul_f32 v[158:159], v[158:159], v[194:195] op_sel_hi:[1,0]
	v_pk_mul_f32 v[160:161], v[160:161], v[194:195] op_sel_hi:[1,0]
	v_pk_mul_f32 v[162:163], v[162:163], v[194:195] op_sel_hi:[1,0]
	v_pk_mul_f32 v[164:165], v[164:165], v[194:195] op_sel_hi:[1,0]
	v_pk_mul_f32 v[166:167], v[166:167], v[194:195] op_sel_hi:[1,0]
	v_pk_mul_f32 v[168:169], v[168:169], v[194:195] op_sel_hi:[1,0]
	v_exp_f32_e32 v128, v128
	v_exp_f32_e32 v129, v129
	v_exp_f32_e32 v132, v132
	v_exp_f32_e32 v133, v133
	v_exp_f32_e32 v158, v158
	v_exp_f32_e32 v159, v159
	v_exp_f32_e32 v160, v160
	v_exp_f32_e32 v161, v161
	v_exp_f32_e32 v162, v162
	v_exp_f32_e32 v163, v163
	v_exp_f32_e32 v164, v164
	v_exp_f32_e32 v165, v165
	v_exp_f32_e32 v166, v166
	v_exp_f32_e32 v167, v167
	v_exp_f32_e32 v168, v168
	v_exp_f32_e32 v169, v169
	v_pk_add_f32 v[128:129], v[128:129], 1.0 op_sel_hi:[1,0]
	v_pk_add_f32 v[132:133], v[132:133], 1.0 op_sel_hi:[1,0]
	v_pk_add_f32 v[158:159], v[158:159], 1.0 op_sel_hi:[1,0]
	v_pk_add_f32 v[160:161], v[160:161], 1.0 op_sel_hi:[1,0]
	v_pk_add_f32 v[162:163], v[162:163], 1.0 op_sel_hi:[1,0]
	v_pk_add_f32 v[164:165], v[164:165], 1.0 op_sel_hi:[1,0]
	v_pk_add_f32 v[166:167], v[166:167], 1.0 op_sel_hi:[1,0]
	v_pk_add_f32 v[168:169], v[168:169], 1.0 op_sel_hi:[1,0]
	v_rcp_f32_e32 v128, v128
	v_rcp_f32_e32 v129, v129
	v_rcp_f32_e32 v132, v132
	v_rcp_f32_e32 v133, v133
	v_rcp_f32_e32 v158, v158
	v_rcp_f32_e32 v159, v159
	v_rcp_f32_e32 v160, v160
	v_rcp_f32_e32 v161, v161
	v_rcp_f32_e32 v162, v162
	v_rcp_f32_e32 v163, v163
	v_rcp_f32_e32 v164, v164
	v_rcp_f32_e32 v165, v165
	v_rcp_f32_e32 v166, v166
	v_rcp_f32_e32 v167, v167
	v_rcp_f32_e32 v168, v168
	v_rcp_f32_e32 v169, v169
	v_pk_mul_f32 v[128:129], v[124:125], v[128:129]
	v_pk_mul_f32 v[132:133], v[126:127], v[132:133]
	v_pk_mul_f32 v[158:159], v[120:121], v[158:159]
	v_pk_mul_f32 v[160:161], v[122:123], v[160:161]
	v_pk_mul_f32 v[162:163], v[116:117], v[162:163]
	v_pk_mul_f32 v[164:165], v[118:119], v[164:165]
	v_pk_mul_f32 v[166:167], v[112:113], v[166:167]
	v_pk_mul_f32 v[168:169], v[114:115], v[168:169]
	v_pk_mul_f32 v[130:131], v[128:129], v[128:129]
	v_pk_mul_f32 v[134:135], v[132:133], v[132:133]
	v_add_f32_e32 v130, v130, v131
	v_add_f32_e32 v130, v134, v130
	v_pk_mul_f32 v[170:171], v[158:159], v[158:159]
	v_add_f32_e32 v130, v135, v130
	v_add_f32_e32 v130, v170, v130
	v_pk_mul_f32 v[172:173], v[160:161], v[160:161]
	v_add_f32_e32 v130, v171, v130
	v_add_f32_e32 v130, v172, v130
	v_pk_mul_f32 v[174:175], v[162:163], v[162:163]
	v_add_f32_e32 v130, v173, v130
	v_add_f32_e32 v130, v130, v174
	v_pk_mul_f32 v[176:177], v[164:165], v[164:165]
	v_add_f32_e32 v130, v175, v130
	v_add_f32_e32 v130, v176, v130
	v_pk_mul_f32 v[178:179], v[166:167], v[166:167]
	v_add_f32_e32 v130, v177, v130
	v_add_f32_e32 v130, v178, v130
	v_pk_mul_f32 v[180:181], v[168:169], v[168:169]
	v_add_f32_e32 v130, v179, v130
	v_add_f32_e32 v130, v180, v130
	v_add_f32_e32 v130, v181, v130
	ds_bpermute_b32 v131, v229, v130
	v_lshl_add_u64 v[180:181], v[140:141], 2, s[18:19]
	v_ashrrev_i32_e32 v157, 31, v156
	v_lshlrev_b64 v[174:175], 10, v[156:157]
	v_lshlrev_b32_e32 v172, 9, v156
	s_waitcnt lgkmcnt(0)
	v_add_f32_e32 v130, v130, v131
	ds_bpermute_b32 v131, v230, v130
	v_mov_b32_e32 v173, v141
	v_cndmask_b32_e64 v157, 0, 1, s[10:11]
	v_cmp_ne_u32_e64 s[0:1], 1, v157
	s_waitcnt lgkmcnt(0)
	v_add_f32_e32 v130, v130, v131
	v_fmamk_f32 v130, v130, 0x3c800000, v188
	v_cmp_gt_f32_e32 vcc, s13, v130
	v_mul_f32_e32 v131, 0x4b800000, v130
	s_nop 0
	v_cndmask_b32_e32 v130, v130, v131, vcc
	v_rsq_f32_e32 v130, v130
	s_nop 0
	v_mul_f32_e32 v131, 0x45800000, v130
	v_cndmask_b32_e32 v170, v130, v131, vcc
	v_pk_mul_f32 v[176:177], v[128:129], v[170:171] op_sel_hi:[1,0]
	v_pk_mul_f32 v[178:179], v[132:133], v[170:171] op_sel_hi:[1,0]
	s_waitcnt vmcnt(0)
	v_mov_b64_e32 v[128:129], v[208:209]
	v_mov_b64_e32 v[130:131], v[210:211]
	v_mov_b64_e32 v[132:133], v[204:205]
	v_mov_b64_e32 v[134:135], v[206:207]
	v_pk_mul_f32 v[158:159], v[158:159], v[170:171] op_sel_hi:[1,0]
	v_pk_mul_f32 v[160:161], v[160:161], v[170:171] op_sel_hi:[1,0]
	s_andn2_b64 vcc, exec, s[10:11]
	v_pk_mul_f32 v[128:129], v[128:129], v[158:159]
	v_lshl_add_u64 v[158:159], s[46:47], 0, v[174:175]
	v_pk_mul_f32 v[134:135], v[134:135], v[178:179]
	v_pk_mul_f32 v[132:133], v[132:133], v[176:177]
	v_pk_mul_f32 v[130:131], v[130:131], v[160:161]
	v_lshl_add_u64 v[158:159], v[140:141], 1, v[158:159]
	v_lshl_add_u64 v[160:161], v[172:173], 2, s[56:57]
	v_cvt_pk_bf16_f32 v174, v132, v133
	v_cvt_pk_bf16_f32 v175, v134, v135
	v_cvt_pk_bf16_f32 v176, v128, v129
	v_cvt_pk_bf16_f32 v177, v130, v131
	global_store_dwordx4 v[158:159], v[174:177], off
	s_cbranch_vccnz .LBB0_221
; __device__ __forceinline__ void st_bf16x8(bf16_t* p, const f32x4 a, const f32x4 b) { uint4 o; o.x = cvt_pk_bf16(a[0], a[1]); o.y = cvt_pk_bf16(a[2], a[3]); o.z = cvt_pk_bf16(b[0], b[1]); o.w = cvt_pk_bf16(b[2], b[3]); *(uint4*)p = o; }
;     __device__ __forceinline__ void row(const f32x4 (&a)[2][2], int row, int pn, int wc, int fq) const {
;     ...
;             for (int bj = 0; bj < 2; ++bj) { const int d = head * 64 + bj * 32 + 8 * fq;
;                 const f32x4 v0 = g[bj][0] * rs * *(const f32x4*)(g_v + d), v1 = g[bj][1] * rs * *(const f32x4*)(g_v + d + 4);
;                 st_bf16x8(pV + (size_t)row * 512 + d, v0, v1);
;                 if (row >= NP && row < NTOK) { float* o = out + O_VS + (size_t)(row - NP) * 512 + d; *(f32x4*)o = v0; *(f32x4*)(o + 4) = v1; } }
	v_lshl_add_u64 v[172:173], v[140:141], 2, v[160:161]
	v_lshl_add_u64 v[174:175], v[172:173], 0, s[70:71]
	v_add_co_u32_e32 v172, vcc, 0x2108000, v172
	s_nop 1
	v_addc_co_u32_e32 v173, vcc, 0, v173, vcc
	global_store_dwordx4 v[172:173], v[132:135], off
	global_store_dwordx4 v[174:175], v[128:131], off offset:16
.LBB0_221:
	v_mov_b64_e32 v[128:129], v[212:213]
	v_mov_b64_e32 v[130:131], v[214:215]
	s_nop 0
	v_mov_b64_e32 v[132:133], v[216:217]
	v_mov_b64_e32 v[134:135], v[218:219]
	v_mov_b32_e32 v171, v170
	v_mov_b32_e32 v172, v170
	v_mov_b32_e32 v173, v170
	v_pk_mul_f32 v[162:163], v[162:163], v[170:171]
	v_pk_mul_f32 v[164:165], v[164:165], v[172:173]
	v_pk_mul_f32 v[166:167], v[166:167], v[170:171]
	v_pk_mul_f32 v[168:169], v[168:169], v[172:173]
	s_and_b64 vcc, exec, s[0:1]
	v_pk_mul_f32 v[130:131], v[164:165], v[130:131]
	v_pk_mul_f32 v[128:129], v[162:163], v[128:129]
	v_pk_mul_f32 v[134:135], v[168:169], v[134:135]
	v_pk_mul_f32 v[132:133], v[166:167], v[132:133]
	v_cvt_pk_bf16_f32 v162, v128, v129
	v_cvt_pk_bf16_f32 v163, v130, v131
	v_cvt_pk_bf16_f32 v165, v134, v135
	s_nop 0
	v_cvt_pk_bf16_f32 v164, v132, v133
	global_store_dwordx4 v[158:159], v[162:165], off offset:64
	s_cbranch_vccnz .LBB0_223
	v_lshl_add_u64 v[158:159], v[152:153], 2, v[160:161]
	v_lshl_add_u64 v[160:161], v[158:159], 0, s[70:71]
	v_add_co_u32_e32 v158, vcc, 0x2108000, v158
	s_nop 1
	v_addc_co_u32_e32 v159, vcc, 0, v159, vcc
	global_store_dwordx4 v[158:159], v[128:131], off
	global_store_dwordx4 v[160:161], v[132:135], off offset:16

; __device__ __forceinline__ float gelu_tanh(float x) { const float u = 1.5957691216f * (x + 0.044715f * x * x * x); return x * __builtin_amdgcn_rcpf(1.f + __expf(-u)); }
; __device__ __forceinline__ void st_bf16x8(bf16_t* p, const f32x4 a, const f32x4 b) { uint4 o; o.x = cvt_pk_bf16(a[0], a[1]); o.y = cvt_pk_bf16(a[2], a[3]); o.z = cvt_pk_bf16(b[0], b[1]); o.w = cvt_pk_bf16(b[2], b[3]); *(uint4*)p = o; }
;     __device__ __forceinline__ void row(const f32x4 (&a)[2][2], int row, int pn, int wc, int fq) const {
;     ...
;             const int head = (pn - 2) * 4 + wc;
;             f32x4 g[2][2]; float ss = 0.f;
; #pragma unroll
;             for (int bj = 0; bj < 2; ++bj)
; #pragma unroll
;                 for (int n = 0; n < 2; ++n)
; #pragma unroll
;                     for (int j = 0; j < 4; ++j) { const float t = gelu_tanh(a[bj][n][j]); g[bj][n][j] = t; ss += t * t; }
;             ss += __shfl_xor(ss, 16); ss += __shfl_xor(ss, 32);
;             const float rs = rsqrtf(ss * (1.f / 64.f) + EPS);
; #pragma unroll
;             for (int bj = 0; bj < 2; ++bj) { const int d = head * 64 + bj * 32 + 8 * fq;
;                 const f32x4 v0 = g[bj][0] * rs * *(const f32x4*)(g_v + d), v1 = g[bj][1] * rs * *(const f32x4*)(g_v + d + 4);
;                 st_bf16x8(pV + (size_t)row * 512 + d, v0, v1);
;                 if (row >= NP && row < NTOK) { float* o = out + O_VS + (size_t)(row - NP) * 512 + d; *(f32x4*)o = v0; *(f32x4*)(o + 4) = v1; } }
.LBB0_240:
	s_andn2_b64 vcc, exec, s[0:1]
	s_cbranch_vccnz .LBB0_245
	v_mov_b32_e32 v190, 0x3d372713
	v_mov_b32_e32 v192, 0xbfcc422a
	v_mov_b32_e32 v194, 0x3fb8aa3b
	v_pk_mul_f32 v[112:113], v[108:109], v[190:191] op_sel_hi:[1,0]
	v_pk_mul_f32 v[116:117], v[110:111], v[190:191] op_sel_hi:[1,0]
	v_pk_mul_f32 v[122:123], v[104:105], v[190:191] op_sel_hi:[1,0]
	v_pk_mul_f32 v[124:125], v[106:107], v[190:191] op_sel_hi:[1,0]
	v_pk_mul_f32 v[126:127], v[100:101], v[190:191] op_sel_hi:[1,0]
	v_pk_mul_f32 v[128:129], v[102:103], v[190:191] op_sel_hi:[1,0]
	v_pk_mul_f32 v[130:131], v[96:97], v[190:191] op_sel_hi:[1,0]
	v_pk_mul_f32 v[132:133], v[98:99], v[190:191] op_sel_hi:[1,0]
	v_pk_mul_f32 v[112:113], v[108:109], v[112:113]
	v_pk_mul_f32 v[116:117], v[110:111], v[116:117]
	v_pk_mul_f32 v[122:123], v[104:105], v[122:123]
	v_pk_mul_f32 v[124:125], v[106:107], v[124:125]
	v_pk_mul_f32 v[126:127], v[100:101], v[126:127]
	v_pk_mul_f32 v[128:129], v[102:103], v[128:129]
	v_pk_mul_f32 v[130:131], v[96:97], v[130:131]
	v_pk_mul_f32 v[132:133], v[98:99], v[132:133]
	v_pk_fma_f32 v[112:113], v[108:109], v[112:113], v[108:109]
	v_pk_fma_f32 v[116:117], v[110:111], v[116:117], v[110:111]
	v_pk_fma_f32 v[122:123], v[104:105], v[122:123], v[104:105]
	v_pk_fma_f32 v[124:125], v[106:107], v[124:125], v[106:107]
	v_pk_fma_f32 v[126:127], v[100:101], v[126:127], v[100:101]
	v_pk_fma_f32 v[128:129], v[102:103], v[128:129], v[102:103]
	v_pk_fma_f32 v[130:131], v[96:97], v[130:131], v[96:97]
	v_pk_fma_f32 v[132:133], v[98:99], v[132:133], v[98:99]
	v_pk_mul_f32 v[112:113], v[112:113], v[192:193] op_sel_hi:[1,0]
	v_pk_mul_f32 v[116:117], v[116:117], v[192:193] op_sel_hi:[1,0]
	v_pk_mul_f32 v[122:123], v[122:123], v[192:193] op_sel_hi:[1,0]
	v_pk_mul_f32 v[124:125], v[124:125], v[192:193] op_sel_hi:[1,0]
	v_pk_mul_f32 v[126:127], v[126:127], v[192:193] op_sel_hi:[1,0]
	v_pk_mul_f32 v[128:129], v[128:129], v[192:193] op_sel_hi:[1,0]
	v_pk_mul_f32 v[130:131], v[130:131], v[192:193] op_sel_hi:[1,0]
	v_pk_mul_f32 v[132:133], v[132:133], v[192:193] op_sel_hi:[1,0]
	v_pk_mul_f32 v[112:113], v[112:113], v[194:195] op_sel_hi:[1,0]
	v_pk_mul_f32 v[116:117], v[116:117], v[194:195] op_sel_hi:[1,0]
	v_pk_mul_f32 v[122:123], v[122:123], v[194:195] op_sel_hi:[1,0]
	v_pk_mul_f32 v[124:125], v[124:125], v[194:195] op_sel_hi:[1,0]
	v_pk_mul_f32 v[126:127], v[126:127], v[194:195] op_sel_hi:[1,0]
	v_pk_mul_f32 v[128:129], v[128:129], v[194:195] op_sel_hi:[1,0]
	v_pk_mul_f32 v[130:131], v[130:131], v[194:195] op_sel_hi:[1,0]
	v_pk_mul_f32 v[132:133], v[132:133], v[194:195] op_sel_hi:[1,0]
	v_exp_f32_e32 v112, v112
	v_exp_f32_e32 v113, v113
	v_exp_f32_e32 v116, v116
	v_exp_f32_e32 v117, v117
	v_exp_f32_e32 v122, v122
	v_exp_f32_e32 v123, v123
	v_exp_f32_e32 v124, v124
	v_exp_f32_e32 v125, v125
	v_exp_f32_e32 v126, v126
	v_exp_f32_e32 v127, v127
	v_exp_f32_e32 v128, v128
	v_exp_f32_e32 v129, v129
	v_exp_f32_e32 v130, v130
	v_exp_f32_e32 v131, v131
	v_exp_f32_e32 v132, v132
	v_exp_f32_e32 v133, v133
	v_pk_add_f32 v[112:113], v[112:113], 1.0 op_sel_hi:[1,0]
	v_pk_add_f32 v[116:117], v[116:117], 1.0 op_sel_hi:[1,0]
	v_pk_add_f32 v[122:123], v[122:123], 1.0 op_sel_hi:[1,0]
	v_pk_add_f32 v[124:125], v[124:125], 1.0 op_sel_hi:[1,0]
	v_pk_add_f32 v[126:127], v[126:127], 1.0 op_sel_hi:[1,0]
	v_pk_add_f32 v[128:129], v[128:129], 1.0 op_sel_hi:[1,0]
	v_pk_add_f32 v[130:131], v[130:131], 1.0 op_sel_hi:[1,0]
	v_pk_add_f32 v[132:133], v[132:133], 1.0 op_sel_hi:[1,0]
	v_rcp_f32_e32 v112, v112
	v_rcp_f32_e32 v113, v113
	v_rcp_f32_e32 v116, v116
	v_rcp_f32_e32 v117, v117
	v_rcp_f32_e32 v122, v122
	v_rcp_f32_e32 v123, v123
	v_rcp_f32_e32 v124, v124
	v_rcp_f32_e32 v125, v125
	v_rcp_f32_e32 v126, v126
	v_rcp_f32_e32 v127, v127
	v_rcp_f32_e32 v128, v128
	v_rcp_f32_e32 v129, v129
	v_rcp_f32_e32 v130, v130
	v_rcp_f32_e32 v131, v131
	v_rcp_f32_e32 v132, v132
	v_rcp_f32_e32 v133, v133
	v_pk_mul_f32 v[112:113], v[108:109], v[112:113]
	v_pk_mul_f32 v[116:117], v[110:111], v[116:117]
	v_pk_mul_f32 v[122:123], v[104:105], v[122:123]
	v_pk_mul_f32 v[124:125], v[106:107], v[124:125]
	v_pk_mul_f32 v[126:127], v[100:101], v[126:127]
	v_pk_mul_f32 v[128:129], v[102:103], v[128:129]
	v_pk_mul_f32 v[130:131], v[96:97], v[130:131]
	v_pk_mul_f32 v[132:133], v[98:99], v[132:133]
	v_pk_mul_f32 v[114:115], v[112:113], v[112:113]
	v_pk_mul_f32 v[118:119], v[116:117], v[116:117]
	v_add_f32_e32 v114, v114, v115
	v_add_f32_e32 v114, v118, v114
	v_pk_mul_f32 v[134:135], v[122:123], v[122:123]
	v_add_f32_e32 v114, v119, v114
	v_add_f32_e32 v114, v134, v114
	v_pk_mul_f32 v[158:159], v[124:125], v[124:125]
	v_add_f32_e32 v114, v135, v114
	v_add_f32_e32 v114, v158, v114
	v_pk_mul_f32 v[160:161], v[126:127], v[126:127]
	v_add_f32_e32 v114, v159, v114
	v_add_f32_e32 v114, v114, v160
	v_pk_mul_f32 v[162:163], v[128:129], v[128:129]
	v_add_f32_e32 v114, v161, v114
	v_add_f32_e32 v114, v162, v114
	v_pk_mul_f32 v[164:165], v[130:131], v[130:131]
	v_add_f32_e32 v114, v163, v114
	v_add_f32_e32 v114, v164, v114
	v_pk_mul_f32 v[166:167], v[132:133], v[132:133]
	v_add_f32_e32 v114, v165, v114
	v_add_f32_e32 v114, v166, v114
	v_add_f32_e32 v114, v167, v114
	ds_bpermute_b32 v115, v229, v114
	v_lshl_add_u64 v[166:167], v[140:141], 2, s[18:19]
	v_ashrrev_i32_e32 v121, 31, v120
	v_lshlrev_b64 v[160:161], 10, v[120:121]
	v_lshlrev_b32_e32 v158, 9, v120
	s_waitcnt lgkmcnt(0)
	v_add_f32_e32 v114, v114, v115
	ds_bpermute_b32 v115, v230, v114
	v_mov_b32_e32 v159, v141
	v_cndmask_b32_e64 v121, 0, 1, s[10:11]
	v_cmp_ne_u32_e64 s[0:1], 1, v121
	s_waitcnt lgkmcnt(0)
	v_add_f32_e32 v114, v114, v115
	v_fmamk_f32 v114, v114, 0x3c800000, v188
	v_cmp_gt_f32_e32 vcc, s13, v114
	v_mul_f32_e32 v115, 0x4b800000, v114
	s_nop 0
	v_cndmask_b32_e32 v114, v114, v115, vcc
	v_rsq_f32_e32 v114, v114
	s_nop 0
	v_mul_f32_e32 v115, 0x45800000, v114
	v_cndmask_b32_e32 v134, v114, v115, vcc
	v_pk_mul_f32 v[162:163], v[112:113], v[134:135] op_sel_hi:[1,0]
	v_pk_mul_f32 v[164:165], v[116:117], v[134:135] op_sel_hi:[1,0]
	v_mov_b64_e32 v[112:113], v[208:209]
	v_mov_b64_e32 v[114:115], v[210:211]
	v_mov_b64_e32 v[116:117], v[204:205]
	v_mov_b64_e32 v[118:119], v[206:207]
	v_pk_mul_f32 v[122:123], v[122:123], v[134:135] op_sel_hi:[1,0]
	v_pk_mul_f32 v[124:125], v[124:125], v[134:135] op_sel_hi:[1,0]
	s_andn2_b64 vcc, exec, s[10:11]
	v_pk_mul_f32 v[112:113], v[112:113], v[122:123]
	v_lshl_add_u64 v[122:123], s[46:47], 0, v[160:161]
	v_pk_mul_f32 v[118:119], v[118:119], v[164:165]
	v_pk_mul_f32 v[116:117], v[116:117], v[162:163]
	v_pk_mul_f32 v[114:115], v[114:115], v[124:125]
	v_lshl_add_u64 v[122:123], v[140:141], 1, v[122:123]
	v_lshl_add_u64 v[124:125], v[158:159], 2, s[56:57]
	v_cvt_pk_bf16_f32 v160, v116, v117
	v_cvt_pk_bf16_f32 v161, v118, v119
	v_cvt_pk_bf16_f32 v162, v112, v113
	v_cvt_pk_bf16_f32 v163, v114, v115
	global_store_dwordx4 v[122:123], v[160:163], off
	s_cbranch_vccnz .LBB0_243
; __device__ __forceinline__ void st_bf16x8(bf16_t* p, const f32x4 a, const f32x4 b) { uint4 o; o.x = cvt_pk_bf16(a[0], a[1]); o.y = cvt_pk_bf16(a[2], a[3]); o.z = cvt_pk_bf16(b[0], b[1]); o.w = cvt_pk_bf16(b[2], b[3]); *(uint4*)p = o; }
;     __device__ __forceinline__ void row(const f32x4 (&a)[2][2], int row, int pn, int wc, int fq) const {
;     ...
;             for (int bj = 0; bj < 2; ++bj) { const int d = head * 64 + bj * 32 + 8 * fq;
;                 const f32x4 v0 = g[bj][0] * rs * *(const f32x4*)(g_v + d), v1 = g[bj][1] * rs * *(const f32x4*)(g_v + d + 4);
;                 st_bf16x8(pV + (size_t)row * 512 + d, v0, v1);
;                 if (row >= NP && row < NTOK) { float* o = out + O_VS + (size_t)(row - NP) * 512 + d; *(f32x4*)o = v0; *(f32x4*)(o + 4) = v1; } }
	v_lshl_add_u64 v[158:159], v[140:141], 2, v[124:125]
	v_lshl_add_u64 v[160:161], v[158:159], 0, s[70:71]
	v_add_co_u32_e32 v158, vcc, 0x2108000, v158
	s_nop 1
	v_addc_co_u32_e32 v159, vcc, 0, v159, vcc
	global_store_dwordx4 v[158:159], v[116:119], off
	global_store_dwordx4 v[160:161], v[112:115], off offset:16
.LBB0_243:
	v_mov_b64_e32 v[112:113], v[212:213]
	v_mov_b64_e32 v[114:115], v[214:215]
	s_nop 0
	v_mov_b64_e32 v[116:117], v[216:217]
	v_mov_b64_e32 v[118:119], v[218:219]
	v_mov_b32_e32 v135, v134
	v_mov_b32_e32 v158, v134
	v_mov_b32_e32 v159, v134
	v_pk_mul_f32 v[126:127], v[126:127], v[134:135]
	v_pk_mul_f32 v[128:129], v[128:129], v[158:159]
	v_pk_mul_f32 v[130:131], v[130:131], v[134:135]
	v_pk_mul_f32 v[132:133], v[132:133], v[158:159]
	s_and_b64 vcc, exec, s[0:1]
	v_pk_mul_f32 v[114:115], v[128:129], v[114:115]
	v_pk_mul_f32 v[112:113], v[126:127], v[112:113]
	v_pk_mul_f32 v[118:119], v[132:133], v[118:119]
	v_pk_mul_f32 v[116:117], v[130:131], v[116:117]
	v_cvt_pk_bf16_f32 v126, v112, v113
	v_cvt_pk_bf16_f32 v127, v114, v115
	v_cvt_pk_bf16_f32 v129, v118, v119
	s_nop 0
	v_cvt_pk_bf16_f32 v128, v116, v117
	global_store_dwordx4 v[122:123], v[126:129], off offset:64
	s_cbranch_vccnz .LBB0_245
	v_lshl_add_u64 v[122:123], v[152:153], 2, v[124:125]
	v_lshl_add_u64 v[124:125], v[122:123], 0, s[70:71]
	v_add_co_u32_e32 v122, vcc, 0x2108000, v122
	s_nop 1
	v_addc_co_u32_e32 v123, vcc, 0, v123, vcc
	global_store_dwordx4 v[122:123], v[112:115], off
	global_store_dwordx4 v[124:125], v[116:119], off offset:16

; __device__ __forceinline__ float gelu_tanh(float x) { const float u = 1.5957691216f * (x + 0.044715f * x * x * x); return x * __builtin_amdgcn_rcpf(1.f + __expf(-u)); }
; __device__ __forceinline__ void st_bf16x8(bf16_t* p, const f32x4 a, const f32x4 b) { uint4 o; o.x = cvt_pk_bf16(a[0], a[1]); o.y = cvt_pk_bf16(a[2], a[3]); o.z = cvt_pk_bf16(b[0], b[1]); o.w = cvt_pk_bf16(b[2], b[3]); *(uint4*)p = o; }
;     __device__ __forceinline__ void row(const f32x4 (&a)[2][2], int row, int pn, int wc, int fq) const {
;     ...
;             const int head = (pn - 2) * 4 + wc;
;             f32x4 g[2][2]; float ss = 0.f;
; #pragma unroll
;             for (int bj = 0; bj < 2; ++bj)
; #pragma unroll
;                 for (int n = 0; n < 2; ++n)
; #pragma unroll
;                     for (int j = 0; j < 4; ++j) { const float t = gelu_tanh(a[bj][n][j]); g[bj][n][j] = t; ss += t * t; }
;             ss += __shfl_xor(ss, 16); ss += __shfl_xor(ss, 32);
;             const float rs = rsqrtf(ss * (1.f / 64.f) + EPS);
; #pragma unroll
;             for (int bj = 0; bj < 2; ++bj) { const int d = head * 64 + bj * 32 + 8 * fq;
;                 const f32x4 v0 = g[bj][0] * rs * *(const f32x4*)(g_v + d), v1 = g[bj][1] * rs * *(const f32x4*)(g_v + d + 4);
;                 st_bf16x8(pV + (size_t)row * 512 + d, v0, v1);
;                 if (row >= NP && row < NTOK) { float* o = out + O_VS + (size_t)(row - NP) * 512 + d; *(f32x4*)o = v0; *(f32x4*)(o + 4) = v1; } }
.LBB0_255:
	s_andn2_b64 vcc, exec, s[0:1]
	s_cbranch_vccnz .LBB0_260
	v_mov_b32_e32 v190, 0x3d372713
	v_mov_b32_e32 v192, 0xbfcc422a
	v_mov_b32_e32 v194, 0x3fb8aa3b
	v_pk_mul_f32 v[96:97], v[92:93], v[190:191] op_sel_hi:[1,0]
	v_pk_mul_f32 v[100:101], v[94:95], v[190:191] op_sel_hi:[1,0]
	v_pk_mul_f32 v[106:107], v[88:89], v[190:191] op_sel_hi:[1,0]
	v_pk_mul_f32 v[108:109], v[90:91], v[190:191] op_sel_hi:[1,0]
	v_pk_mul_f32 v[110:111], v[84:85], v[190:191] op_sel_hi:[1,0]
	v_pk_mul_f32 v[112:113], v[86:87], v[190:191] op_sel_hi:[1,0]
	v_pk_mul_f32 v[114:115], v[80:81], v[190:191] op_sel_hi:[1,0]
	v_pk_mul_f32 v[116:117], v[82:83], v[190:191] op_sel_hi:[1,0]
	v_pk_mul_f32 v[96:97], v[92:93], v[96:97]
	v_pk_mul_f32 v[100:101], v[94:95], v[100:101]
	v_pk_mul_f32 v[106:107], v[88:89], v[106:107]
	v_pk_mul_f32 v[108:109], v[90:91], v[108:109]
	v_pk_mul_f32 v[110:111], v[84:85], v[110:111]
	v_pk_mul_f32 v[112:113], v[86:87], v[112:113]
	v_pk_mul_f32 v[114:115], v[80:81], v[114:115]
	v_pk_mul_f32 v[116:117], v[82:83], v[116:117]
	v_pk_fma_f32 v[96:97], v[92:93], v[96:97], v[92:93]
	v_pk_fma_f32 v[100:101], v[94:95], v[100:101], v[94:95]
	v_pk_fma_f32 v[106:107], v[88:89], v[106:107], v[88:89]
	v_pk_fma_f32 v[108:109], v[90:91], v[108:109], v[90:91]
	v_pk_fma_f32 v[110:111], v[84:85], v[110:111], v[84:85]
	v_pk_fma_f32 v[112:113], v[86:87], v[112:113], v[86:87]
	v_pk_fma_f32 v[114:115], v[80:81], v[114:115], v[80:81]
	v_pk_fma_f32 v[116:117], v[82:83], v[116:117], v[82:83]
	v_pk_mul_f32 v[96:97], v[96:97], v[192:193] op_sel_hi:[1,0]
	v_pk_mul_f32 v[100:101], v[100:101], v[192:193] op_sel_hi:[1,0]
	v_pk_mul_f32 v[106:107], v[106:107], v[192:193] op_sel_hi:[1,0]
	v_pk_mul_f32 v[108:109], v[108:109], v[192:193] op_sel_hi:[1,0]
	v_pk_mul_f32 v[110:111], v[110:111], v[192:193] op_sel_hi:[1,0]
	v_pk_mul_f32 v[112:113], v[112:113], v[192:193] op_sel_hi:[1,0]
	v_pk_mul_f32 v[114:115], v[114:115], v[192:193] op_sel_hi:[1,0]
	v_pk_mul_f32 v[116:117], v[116:117], v[192:193] op_sel_hi:[1,0]
	v_pk_mul_f32 v[96:97], v[96:97], v[194:195] op_sel_hi:[1,0]
	v_pk_mul_f32 v[100:101], v[100:101], v[194:195] op_sel_hi:[1,0]
	v_pk_mul_f32 v[106:107], v[106:107], v[194:195] op_sel_hi:[1,0]
	v_pk_mul_f32 v[108:109], v[108:109], v[194:195] op_sel_hi:[1,0]
	v_pk_mul_f32 v[110:111], v[110:111], v[194:195] op_sel_hi:[1,0]
	v_pk_mul_f32 v[112:113], v[112:113], v[194:195] op_sel_hi:[1,0]
	v_pk_mul_f32 v[114:115], v[114:115], v[194:195] op_sel_hi:[1,0]
	v_pk_mul_f32 v[116:117], v[116:117], v[194:195] op_sel_hi:[1,0]
	v_exp_f32_e32 v96, v96
	v_exp_f32_e32 v97, v97
	v_exp_f32_e32 v100, v100
	v_exp_f32_e32 v101, v101
	v_exp_f32_e32 v106, v106
	v_exp_f32_e32 v107, v107
	v_exp_f32_e32 v108, v108
	v_exp_f32_e32 v109, v109
	v_exp_f32_e32 v110, v110
	v_exp_f32_e32 v111, v111
	v_exp_f32_e32 v112, v112
	v_exp_f32_e32 v113, v113
	v_exp_f32_e32 v114, v114
	v_exp_f32_e32 v115, v115
	v_exp_f32_e32 v116, v116
	v_exp_f32_e32 v117, v117
	v_pk_add_f32 v[96:97], v[96:97], 1.0 op_sel_hi:[1,0]
	v_pk_add_f32 v[100:101], v[100:101], 1.0 op_sel_hi:[1,0]
	v_pk_add_f32 v[106:107], v[106:107], 1.0 op_sel_hi:[1,0]
	v_pk_add_f32 v[108:109], v[108:109], 1.0 op_sel_hi:[1,0]
	v_pk_add_f32 v[110:111], v[110:111], 1.0 op_sel_hi:[1,0]
	v_pk_add_f32 v[112:113], v[112:113], 1.0 op_sel_hi:[1,0]
	v_pk_add_f32 v[114:115], v[114:115], 1.0 op_sel_hi:[1,0]
	v_pk_add_f32 v[116:117], v[116:117], 1.0 op_sel_hi:[1,0]
	v_rcp_f32_e32 v96, v96
	v_rcp_f32_e32 v97, v97
	v_rcp_f32_e32 v100, v100
	v_rcp_f32_e32 v101, v101
	v_rcp_f32_e32 v106, v106
	v_rcp_f32_e32 v107, v107
	v_rcp_f32_e32 v108, v108
	v_rcp_f32_e32 v109, v109
	v_rcp_f32_e32 v110, v110
	v_rcp_f32_e32 v111, v111
	v_rcp_f32_e32 v112, v112
	v_rcp_f32_e32 v113, v113
	v_rcp_f32_e32 v114, v114
	v_rcp_f32_e32 v115, v115
	v_rcp_f32_e32 v116, v116
	v_rcp_f32_e32 v117, v117
	v_pk_mul_f32 v[96:97], v[92:93], v[96:97]
	v_pk_mul_f32 v[100:101], v[94:95], v[100:101]
	v_pk_mul_f32 v[106:107], v[88:89], v[106:107]
	v_pk_mul_f32 v[108:109], v[90:91], v[108:109]
	v_pk_mul_f32 v[110:111], v[84:85], v[110:111]
	v_pk_mul_f32 v[112:113], v[86:87], v[112:113]
	v_pk_mul_f32 v[114:115], v[80:81], v[114:115]
	v_pk_mul_f32 v[116:117], v[82:83], v[116:117]
	v_pk_mul_f32 v[98:99], v[96:97], v[96:97]
	v_pk_mul_f32 v[102:103], v[100:101], v[100:101]
	v_add_f32_e32 v98, v98, v99
	v_add_f32_e32 v98, v102, v98
	v_pk_mul_f32 v[118:119], v[106:107], v[106:107]
	v_add_f32_e32 v98, v103, v98
	v_add_f32_e32 v98, v118, v98
	v_pk_mul_f32 v[120:121], v[108:109], v[108:109]
	v_add_f32_e32 v98, v119, v98
	v_add_f32_e32 v98, v120, v98
	v_pk_mul_f32 v[122:123], v[110:111], v[110:111]
	v_add_f32_e32 v98, v121, v98
	v_add_f32_e32 v98, v98, v122
	v_pk_mul_f32 v[124:125], v[112:113], v[112:113]
	v_add_f32_e32 v98, v123, v98
	v_add_f32_e32 v98, v124, v98
	v_pk_mul_f32 v[126:127], v[114:115], v[114:115]
	v_add_f32_e32 v98, v125, v98
	v_add_f32_e32 v98, v126, v98
	v_pk_mul_f32 v[128:129], v[116:117], v[116:117]
	v_add_f32_e32 v98, v127, v98
	v_add_f32_e32 v98, v128, v98
	v_add_f32_e32 v98, v129, v98
	ds_bpermute_b32 v99, v229, v98
	v_lshl_add_u64 v[128:129], v[140:141], 2, s[18:19]
	v_ashrrev_i32_e32 v105, 31, v104
	v_lshlrev_b64 v[122:123], 10, v[104:105]
	v_lshlrev_b32_e32 v120, 9, v104
	s_waitcnt lgkmcnt(0)
	v_add_f32_e32 v98, v98, v99
	ds_bpermute_b32 v99, v230, v98
	v_mov_b32_e32 v121, v141
	v_cndmask_b32_e64 v105, 0, 1, s[10:11]
	v_cmp_ne_u32_e64 s[0:1], 1, v105
	s_waitcnt lgkmcnt(0)
	v_add_f32_e32 v98, v98, v99
	v_fmamk_f32 v98, v98, 0x3c800000, v188
	v_cmp_gt_f32_e32 vcc, s13, v98
	v_mul_f32_e32 v99, 0x4b800000, v98
	s_nop 0
	v_cndmask_b32_e32 v98, v98, v99, vcc
	v_rsq_f32_e32 v98, v98
	s_nop 0
	v_mul_f32_e32 v99, 0x45800000, v98
	v_cndmask_b32_e32 v118, v98, v99, vcc
	v_pk_mul_f32 v[124:125], v[96:97], v[118:119] op_sel_hi:[1,0]
	v_pk_mul_f32 v[126:127], v[100:101], v[118:119] op_sel_hi:[1,0]
	v_mov_b64_e32 v[96:97], v[208:209]
	v_mov_b64_e32 v[98:99], v[210:211]
	v_mov_b64_e32 v[100:101], v[204:205]
	v_mov_b64_e32 v[102:103], v[206:207]
	v_pk_mul_f32 v[106:107], v[106:107], v[118:119] op_sel_hi:[1,0]
	v_pk_mul_f32 v[108:109], v[108:109], v[118:119] op_sel_hi:[1,0]
	s_andn2_b64 vcc, exec, s[10:11]
	v_pk_mul_f32 v[96:97], v[96:97], v[106:107]
	v_lshl_add_u64 v[106:107], s[46:47], 0, v[122:123]
	v_pk_mul_f32 v[102:103], v[102:103], v[126:127]
	v_pk_mul_f32 v[100:101], v[100:101], v[124:125]
	v_pk_mul_f32 v[98:99], v[98:99], v[108:109]
	v_lshl_add_u64 v[106:107], v[140:141], 1, v[106:107]
	v_lshl_add_u64 v[108:109], v[120:121], 2, s[56:57]
	v_cvt_pk_bf16_f32 v122, v100, v101
	v_cvt_pk_bf16_f32 v123, v102, v103
	v_cvt_pk_bf16_f32 v124, v96, v97
	v_cvt_pk_bf16_f32 v125, v98, v99
	global_store_dwordx4 v[106:107], v[122:125], off
	s_cbranch_vccnz .LBB0_258
	v_lshl_add_u64 v[120:121], v[140:141], 2, v[108:109]
	v_lshl_add_u64 v[122:123], v[120:121], 0, s[70:71]
	v_add_co_u32_e32 v120, vcc, 0x2108000, v120
	s_nop 1
	v_addc_co_u32_e32 v121, vcc, 0, v121, vcc
	global_store_dwordx4 v[120:121], v[100:103], off
	global_store_dwordx4 v[122:123], v[96:99], off offset:16
; __device__ __forceinline__ void st_bf16x8(bf16_t* p, const f32x4 a, const f32x4 b) { uint4 o; o.x = cvt_pk_bf16(a[0], a[1]); o.y = cvt_pk_bf16(a[2], a[3]); o.z = cvt_pk_bf16(b[0], b[1]); o.w = cvt_pk_bf16(b[2], b[3]); *(uint4*)p = o; }
;     __device__ __forceinline__ void row(const f32x4 (&a)[2][2], int row, int pn, int wc, int fq) const {
;     ...
;             for (int bj = 0; bj < 2; ++bj) { const int d = head * 64 + bj * 32 + 8 * fq;
;                 const f32x4 v0 = g[bj][0] * rs * *(const f32x4*)(g_v + d), v1 = g[bj][1] * rs * *(const f32x4*)(g_v + d + 4);
;                 st_bf16x8(pV + (size_t)row * 512 + d, v0, v1);
;                 if (row >= NP && row < NTOK) { float* o = out + O_VS + (size_t)(row - NP) * 512 + d; *(f32x4*)o = v0; *(f32x4*)(o + 4) = v1; } }
.LBB0_258:
	v_mov_b64_e32 v[96:97], v[212:213]
	v_mov_b64_e32 v[98:99], v[214:215]
	s_nop 0
	v_mov_b64_e32 v[100:101], v[216:217]
	v_mov_b64_e32 v[102:103], v[218:219]
	v_mov_b32_e32 v119, v118
	v_mov_b32_e32 v120, v118
	v_mov_b32_e32 v121, v118
	v_pk_mul_f32 v[110:111], v[110:111], v[118:119]
	v_pk_mul_f32 v[112:113], v[112:113], v[120:121]
	v_pk_mul_f32 v[114:115], v[114:115], v[118:119]
	v_pk_mul_f32 v[116:117], v[116:117], v[120:121]
	s_and_b64 vcc, exec, s[0:1]
	v_pk_mul_f32 v[98:99], v[112:113], v[98:99]
	v_pk_mul_f32 v[96:97], v[110:111], v[96:97]
	v_pk_mul_f32 v[102:103], v[116:117], v[102:103]
	v_pk_mul_f32 v[100:101], v[114:115], v[100:101]
	v_cvt_pk_bf16_f32 v110, v96, v97
	v_cvt_pk_bf16_f32 v111, v98, v99
	v_cvt_pk_bf16_f32 v113, v102, v103
	s_nop 0
	v_cvt_pk_bf16_f32 v112, v100, v101
	global_store_dwordx4 v[106:107], v[110:113], off offset:64
	s_cbranch_vccnz .LBB0_260
	v_lshl_add_u64 v[106:107], v[152:153], 2, v[108:109]
	v_lshl_add_u64 v[108:109], v[106:107], 0, s[70:71]
	v_add_co_u32_e32 v106, vcc, 0x2108000, v106
	s_nop 1
	v_addc_co_u32_e32 v107, vcc, 0, v107, vcc
	global_store_dwordx4 v[106:107], v[96:99], off
	global_store_dwordx4 v[108:109], v[100:103], off offset:16

; __device__ __forceinline__ float gelu_tanh(float x) { const float u = 1.5957691216f * (x + 0.044715f * x * x * x); return x * __builtin_amdgcn_rcpf(1.f + __expf(-u)); }
; __device__ __forceinline__ void st_bf16x8(bf16_t* p, const f32x4 a, const f32x4 b) { uint4 o; o.x = cvt_pk_bf16(a[0], a[1]); o.y = cvt_pk_bf16(a[2], a[3]); o.z = cvt_pk_bf16(b[0], b[1]); o.w = cvt_pk_bf16(b[2], b[3]); *(uint4*)p = o; }
;     __device__ __forceinline__ void row(const f32x4 (&a)[2][2], int row, int pn, int wc, int fq) const {
;     ...
;             const int head = (pn - 2) * 4 + wc;
;             f32x4 g[2][2]; float ss = 0.f;
; #pragma unroll
;             for (int bj = 0; bj < 2; ++bj)
; #pragma unroll
;                 for (int n = 0; n < 2; ++n)
; #pragma unroll
;                     for (int j = 0; j < 4; ++j) { const float t = gelu_tanh(a[bj][n][j]); g[bj][n][j] = t; ss += t * t; }
;             ss += __shfl_xor(ss, 16); ss += __shfl_xor(ss, 32);
;             const float rs = rsqrtf(ss * (1.f / 64.f) + EPS);
; #pragma unroll
;             for (int bj = 0; bj < 2; ++bj) { const int d = head * 64 + bj * 32 + 8 * fq;
;                 const f32x4 v0 = g[bj][0] * rs * *(const f32x4*)(g_v + d), v1 = g[bj][1] * rs * *(const f32x4*)(g_v + d + 4);
;                 st_bf16x8(pV + (size_t)row * 512 + d, v0, v1);
;                 if (row >= NP && row < NTOK) { float* o = out + O_VS + (size_t)(row - NP) * 512 + d; *(f32x4*)o = v0; *(f32x4*)(o + 4) = v1; } }
.LBB0_272:
	s_and_b64 vcc, exec, s[0:1]
	s_cbranch_vccz .LBB0_277
	v_mov_b32_e32 v190, 0x3d372713
	v_mov_b32_e32 v192, 0xbfcc422a
	v_mov_b32_e32 v194, 0x3fb8aa3b
	v_pk_mul_f32 v[80:81], v[76:77], v[190:191] op_sel_hi:[1,0]
	v_pk_mul_f32 v[84:85], v[78:79], v[190:191] op_sel_hi:[1,0]
	v_pk_mul_f32 v[90:91], v[72:73], v[190:191] op_sel_hi:[1,0]
	v_pk_mul_f32 v[92:93], v[74:75], v[190:191] op_sel_hi:[1,0]
	v_pk_mul_f32 v[94:95], v[68:69], v[190:191] op_sel_hi:[1,0]
	v_pk_mul_f32 v[96:97], v[70:71], v[190:191] op_sel_hi:[1,0]
	v_pk_mul_f32 v[98:99], v[64:65], v[190:191] op_sel_hi:[1,0]
	v_pk_mul_f32 v[100:101], v[66:67], v[190:191] op_sel_hi:[1,0]
	v_pk_mul_f32 v[80:81], v[76:77], v[80:81]
	v_pk_mul_f32 v[84:85], v[78:79], v[84:85]
	v_pk_mul_f32 v[90:91], v[72:73], v[90:91]
	v_pk_mul_f32 v[92:93], v[74:75], v[92:93]
	v_pk_mul_f32 v[94:95], v[68:69], v[94:95]
	v_pk_mul_f32 v[96:97], v[70:71], v[96:97]
	v_pk_mul_f32 v[98:99], v[64:65], v[98:99]
	v_pk_mul_f32 v[100:101], v[66:67], v[100:101]
	v_pk_fma_f32 v[80:81], v[76:77], v[80:81], v[76:77]
	v_pk_fma_f32 v[84:85], v[78:79], v[84:85], v[78:79]
	v_pk_fma_f32 v[90:91], v[72:73], v[90:91], v[72:73]
	v_pk_fma_f32 v[92:93], v[74:75], v[92:93], v[74:75]
	v_pk_fma_f32 v[94:95], v[68:69], v[94:95], v[68:69]
	v_pk_fma_f32 v[96:97], v[70:71], v[96:97], v[70:71]
	v_pk_fma_f32 v[98:99], v[64:65], v[98:99], v[64:65]
	v_pk_fma_f32 v[100:101], v[66:67], v[100:101], v[66:67]
	v_pk_mul_f32 v[80:81], v[80:81], v[192:193] op_sel_hi:[1,0]
	v_pk_mul_f32 v[84:85], v[84:85], v[192:193] op_sel_hi:[1,0]
	v_pk_mul_f32 v[90:91], v[90:91], v[192:193] op_sel_hi:[1,0]
	v_pk_mul_f32 v[92:93], v[92:93], v[192:193] op_sel_hi:[1,0]
	v_pk_mul_f32 v[94:95], v[94:95], v[192:193] op_sel_hi:[1,0]
	v_pk_mul_f32 v[96:97], v[96:97], v[192:193] op_sel_hi:[1,0]
	v_pk_mul_f32 v[98:99], v[98:99], v[192:193] op_sel_hi:[1,0]
	v_pk_mul_f32 v[100:101], v[100:101], v[192:193] op_sel_hi:[1,0]
	v_pk_mul_f32 v[80:81], v[80:81], v[194:195] op_sel_hi:[1,0]
	v_pk_mul_f32 v[84:85], v[84:85], v[194:195] op_sel_hi:[1,0]
	v_pk_mul_f32 v[90:91], v[90:91], v[194:195] op_sel_hi:[1,0]
	v_pk_mul_f32 v[92:93], v[92:93], v[194:195] op_sel_hi:[1,0]
	v_pk_mul_f32 v[94:95], v[94:95], v[194:195] op_sel_hi:[1,0]
	v_pk_mul_f32 v[96:97], v[96:97], v[194:195] op_sel_hi:[1,0]
	v_pk_mul_f32 v[98:99], v[98:99], v[194:195] op_sel_hi:[1,0]
	v_pk_mul_f32 v[100:101], v[100:101], v[194:195] op_sel_hi:[1,0]
	v_exp_f32_e32 v80, v80
	v_exp_f32_e32 v81, v81
	v_exp_f32_e32 v84, v84
	v_exp_f32_e32 v85, v85
	v_exp_f32_e32 v90, v90
	v_exp_f32_e32 v91, v91
	v_exp_f32_e32 v92, v92
	v_exp_f32_e32 v93, v93
	v_exp_f32_e32 v94, v94
	v_exp_f32_e32 v95, v95
	v_exp_f32_e32 v96, v96
	v_exp_f32_e32 v97, v97
	v_exp_f32_e32 v98, v98
	v_exp_f32_e32 v99, v99
	v_exp_f32_e32 v100, v100
	v_exp_f32_e32 v101, v101
	v_pk_add_f32 v[80:81], v[80:81], 1.0 op_sel_hi:[1,0]
	v_pk_add_f32 v[84:85], v[84:85], 1.0 op_sel_hi:[1,0]
	v_pk_add_f32 v[90:91], v[90:91], 1.0 op_sel_hi:[1,0]
	v_pk_add_f32 v[92:93], v[92:93], 1.0 op_sel_hi:[1,0]
	v_pk_add_f32 v[94:95], v[94:95], 1.0 op_sel_hi:[1,0]
	v_pk_add_f32 v[96:97], v[96:97], 1.0 op_sel_hi:[1,0]
	v_pk_add_f32 v[98:99], v[98:99], 1.0 op_sel_hi:[1,0]
	v_pk_add_f32 v[100:101], v[100:101], 1.0 op_sel_hi:[1,0]
	v_rcp_f32_e32 v80, v80
	v_rcp_f32_e32 v81, v81
	v_rcp_f32_e32 v84, v84
	v_rcp_f32_e32 v85, v85
	v_rcp_f32_e32 v90, v90
	v_rcp_f32_e32 v91, v91
	v_rcp_f32_e32 v92, v92
	v_rcp_f32_e32 v93, v93
	v_rcp_f32_e32 v94, v94
	v_rcp_f32_e32 v95, v95
	v_rcp_f32_e32 v96, v96
	v_rcp_f32_e32 v97, v97
	v_rcp_f32_e32 v98, v98
	v_rcp_f32_e32 v99, v99
	v_rcp_f32_e32 v100, v100
	v_rcp_f32_e32 v101, v101
	v_pk_mul_f32 v[80:81], v[76:77], v[80:81]
	v_pk_mul_f32 v[84:85], v[78:79], v[84:85]
	v_pk_mul_f32 v[90:91], v[72:73], v[90:91]
	v_pk_mul_f32 v[92:93], v[74:75], v[92:93]
	v_pk_mul_f32 v[94:95], v[68:69], v[94:95]
	v_pk_mul_f32 v[96:97], v[70:71], v[96:97]
	v_pk_mul_f32 v[98:99], v[64:65], v[98:99]
	v_pk_mul_f32 v[100:101], v[66:67], v[100:101]
	v_pk_mul_f32 v[82:83], v[80:81], v[80:81]
	v_pk_mul_f32 v[86:87], v[84:85], v[84:85]
	v_add_f32_e32 v82, v82, v83
	v_add_f32_e32 v82, v86, v82
	v_pk_mul_f32 v[102:103], v[90:91], v[90:91]
	v_add_f32_e32 v82, v87, v82
	v_add_f32_e32 v82, v102, v82
	v_pk_mul_f32 v[104:105], v[92:93], v[92:93]
	v_add_f32_e32 v82, v103, v82
	v_add_f32_e32 v82, v104, v82
	v_pk_mul_f32 v[106:107], v[94:95], v[94:95]
	v_add_f32_e32 v82, v105, v82
	v_add_f32_e32 v82, v82, v106
	v_pk_mul_f32 v[108:109], v[96:97], v[96:97]
	v_add_f32_e32 v82, v107, v82
	v_add_f32_e32 v82, v108, v82
	v_pk_mul_f32 v[110:111], v[98:99], v[98:99]
	v_add_f32_e32 v82, v109, v82
	v_add_f32_e32 v82, v110, v82
	v_pk_mul_f32 v[112:113], v[100:101], v[100:101]
	v_add_f32_e32 v82, v111, v82
	v_add_f32_e32 v82, v112, v82
	v_add_f32_e32 v82, v113, v82
	ds_bpermute_b32 v83, v229, v82
	v_lshl_add_u64 v[112:113], v[140:141], 2, s[18:19]
	v_ashrrev_i32_e32 v89, 31, v88
	v_lshlrev_b64 v[106:107], 10, v[88:89]
	v_lshlrev_b32_e32 v104, 9, v88
	s_waitcnt lgkmcnt(0)
	v_add_f32_e32 v82, v82, v83
	ds_bpermute_b32 v83, v230, v82
	v_mov_b32_e32 v105, v141
	v_cndmask_b32_e64 v89, 0, 1, s[10:11]
	v_cmp_ne_u32_e64 s[0:1], 1, v89
	s_waitcnt lgkmcnt(0)
	v_add_f32_e32 v82, v82, v83
	v_fmamk_f32 v82, v82, 0x3c800000, v188
	v_cmp_gt_f32_e32 vcc, s13, v82
	v_mul_f32_e32 v83, 0x4b800000, v82
	s_nop 0
	v_cndmask_b32_e32 v82, v82, v83, vcc
	v_rsq_f32_e32 v82, v82
	s_nop 0
	v_mul_f32_e32 v83, 0x45800000, v82
	v_cndmask_b32_e32 v102, v82, v83, vcc
	v_pk_mul_f32 v[108:109], v[80:81], v[102:103] op_sel_hi:[1,0]
	v_pk_mul_f32 v[110:111], v[84:85], v[102:103] op_sel_hi:[1,0]
	v_mov_b64_e32 v[80:81], v[208:209]
	v_mov_b64_e32 v[82:83], v[210:211]
	v_mov_b64_e32 v[84:85], v[204:205]
	v_mov_b64_e32 v[86:87], v[206:207]
	v_pk_mul_f32 v[90:91], v[90:91], v[102:103] op_sel_hi:[1,0]
	v_pk_mul_f32 v[92:93], v[92:93], v[102:103] op_sel_hi:[1,0]
	s_andn2_b64 vcc, exec, s[10:11]
	v_pk_mul_f32 v[80:81], v[80:81], v[90:91]
	v_lshl_add_u64 v[90:91], s[46:47], 0, v[106:107]
	v_pk_mul_f32 v[86:87], v[86:87], v[110:111]
	v_pk_mul_f32 v[84:85], v[84:85], v[108:109]
	v_pk_mul_f32 v[82:83], v[82:83], v[92:93]
	v_lshl_add_u64 v[90:91], v[140:141], 1, v[90:91]
	v_lshl_add_u64 v[92:93], v[104:105], 2, s[56:57]
	v_cvt_pk_bf16_f32 v106, v84, v85
	v_cvt_pk_bf16_f32 v107, v86, v87
	v_cvt_pk_bf16_f32 v108, v80, v81
	v_cvt_pk_bf16_f32 v109, v82, v83
	global_store_dwordx4 v[90:91], v[106:109], off
	s_cbranch_vccnz .LBB0_275
	v_lshl_add_u64 v[104:105], v[140:141], 2, v[92:93]
	v_lshl_add_u64 v[106:107], v[104:105], 0, s[70:71]
	v_add_co_u32_e32 v104, vcc, 0x2108000, v104
	s_nop 1
	v_addc_co_u32_e32 v105, vcc, 0, v105, vcc
	global_store_dwordx4 v[104:105], v[84:87], off
	global_store_dwordx4 v[106:107], v[80:83], off offset:16
; __device__ __forceinline__ void st_bf16x8(bf16_t* p, const f32x4 a, const f32x4 b) { uint4 o; o.x = cvt_pk_bf16(a[0], a[1]); o.y = cvt_pk_bf16(a[2], a[3]); o.z = cvt_pk_bf16(b[0], b[1]); o.w = cvt_pk_bf16(b[2], b[3]); *(uint4*)p = o; }
;     __device__ __forceinline__ void row(const f32x4 (&a)[2][2], int row, int pn, int wc, int fq) const {
;     ...
;             for (int bj = 0; bj < 2; ++bj) { const int d = head * 64 + bj * 32 + 8 * fq;
;                 const f32x4 v0 = g[bj][0] * rs * *(const f32x4*)(g_v + d), v1 = g[bj][1] * rs * *(const f32x4*)(g_v + d + 4);
;                 st_bf16x8(pV + (size_t)row * 512 + d, v0, v1);
;                 if (row >= NP && row < NTOK) { float* o = out + O_VS + (size_t)(row - NP) * 512 + d; *(f32x4*)o = v0; *(f32x4*)(o + 4) = v1; } }
.LBB0_275:
	v_mov_b64_e32 v[80:81], v[212:213]
	v_mov_b64_e32 v[82:83], v[214:215]
	s_nop 0
	v_mov_b64_e32 v[84:85], v[216:217]
	v_mov_b64_e32 v[86:87], v[218:219]
	v_mov_b32_e32 v103, v102
	v_mov_b32_e32 v104, v102
	v_mov_b32_e32 v105, v102
	v_pk_mul_f32 v[94:95], v[94:95], v[102:103]
	v_pk_mul_f32 v[96:97], v[96:97], v[104:105]
	v_pk_mul_f32 v[98:99], v[98:99], v[102:103]
	v_pk_mul_f32 v[100:101], v[100:101], v[104:105]
	s_and_b64 vcc, exec, s[0:1]
	v_pk_mul_f32 v[82:83], v[96:97], v[82:83]
	v_pk_mul_f32 v[80:81], v[94:95], v[80:81]
	v_pk_mul_f32 v[86:87], v[100:101], v[86:87]
	v_pk_mul_f32 v[84:85], v[98:99], v[84:85]
	v_cvt_pk_bf16_f32 v94, v80, v81
	v_cvt_pk_bf16_f32 v95, v82, v83
	v_cvt_pk_bf16_f32 v97, v86, v87
	s_nop 0
	v_cvt_pk_bf16_f32 v96, v84, v85
	global_store_dwordx4 v[90:91], v[94:97], off offset:64
	s_cbranch_vccnz .LBB0_277
	v_lshl_add_u64 v[90:91], v[152:153], 2, v[92:93]
	v_lshl_add_u64 v[92:93], v[90:91], 0, s[70:71]
	v_add_co_u32_e32 v90, vcc, 0x2108000, v90
	s_nop 1
	v_addc_co_u32_e32 v91, vcc, 0, v91, vcc
	global_store_dwordx4 v[90:91], v[80:83], off
	global_store_dwordx4 v[92:93], v[84:87], off offset:16

; __device__ __forceinline__ float gelu_tanh(float x) { const float u = 1.5957691216f * (x + 0.044715f * x * x * x); return x * __builtin_amdgcn_rcpf(1.f + __expf(-u)); }
; __device__ __forceinline__ void st_bf16x8(bf16_t* p, const f32x4 a, const f32x4 b) { uint4 o; o.x = cvt_pk_bf16(a[0], a[1]); o.y = cvt_pk_bf16(a[2], a[3]); o.z = cvt_pk_bf16(b[0], b[1]); o.w = cvt_pk_bf16(b[2], b[3]); *(uint4*)p = o; }
;     __device__ __forceinline__ void row(const f32x4 (&a)[2][2], int row, int pn, int wc, int fq) const {
;     ...
;             const int head = (pn - 2) * 4 + wc;
;             f32x4 g[2][2]; float ss = 0.f;
; #pragma unroll
;             for (int bj = 0; bj < 2; ++bj)
; #pragma unroll
;                 for (int n = 0; n < 2; ++n)
; #pragma unroll
;                     for (int j = 0; j < 4; ++j) { const float t = gelu_tanh(a[bj][n][j]); g[bj][n][j] = t; ss += t * t; }
;             ss += __shfl_xor(ss, 16); ss += __shfl_xor(ss, 32);
;             const float rs = rsqrtf(ss * (1.f / 64.f) + EPS);
; #pragma unroll
;             for (int bj = 0; bj < 2; ++bj) { const int d = head * 64 + bj * 32 + 8 * fq;
;                 const f32x4 v0 = g[bj][0] * rs * *(const f32x4*)(g_v + d), v1 = g[bj][1] * rs * *(const f32x4*)(g_v + d + 4);
;                 st_bf16x8(pV + (size_t)row * 512 + d, v0, v1);
;                 if (row >= NP && row < NTOK) { float* o = out + O_VS + (size_t)(row - NP) * 512 + d; *(f32x4*)o = v0; *(f32x4*)(o + 4) = v1; } }
.LBB0_295:
	s_andn2_b64 vcc, exec, s[0:1]
	s_cbranch_vccnz .LBB0_301
	v_mov_b32_e32 v190, 0x3d372713
	v_mov_b32_e32 v192, 0xbfcc422a
	v_mov_b32_e32 v194, 0x3fb8aa3b
	v_pk_mul_f32 v[64:65], v[60:61], v[190:191] op_sel_hi:[1,0]
	v_pk_mul_f32 v[68:69], v[62:63], v[190:191] op_sel_hi:[1,0]
	v_pk_mul_f32 v[74:75], v[56:57], v[190:191] op_sel_hi:[1,0]
	v_pk_mul_f32 v[76:77], v[58:59], v[190:191] op_sel_hi:[1,0]
	v_pk_mul_f32 v[78:79], v[52:53], v[190:191] op_sel_hi:[1,0]
	v_pk_mul_f32 v[80:81], v[54:55], v[190:191] op_sel_hi:[1,0]
	v_pk_mul_f32 v[82:83], v[48:49], v[190:191] op_sel_hi:[1,0]
	v_pk_mul_f32 v[84:85], v[50:51], v[190:191] op_sel_hi:[1,0]
	v_pk_mul_f32 v[64:65], v[60:61], v[64:65]
	v_pk_mul_f32 v[68:69], v[62:63], v[68:69]
	v_pk_mul_f32 v[74:75], v[56:57], v[74:75]
	v_pk_mul_f32 v[76:77], v[58:59], v[76:77]
	v_pk_mul_f32 v[78:79], v[52:53], v[78:79]
	v_pk_mul_f32 v[80:81], v[54:55], v[80:81]
	v_pk_mul_f32 v[82:83], v[48:49], v[82:83]
	v_pk_mul_f32 v[84:85], v[50:51], v[84:85]
	v_pk_fma_f32 v[64:65], v[60:61], v[64:65], v[60:61]
	v_pk_fma_f32 v[68:69], v[62:63], v[68:69], v[62:63]
	v_pk_fma_f32 v[74:75], v[56:57], v[74:75], v[56:57]
	v_pk_fma_f32 v[76:77], v[58:59], v[76:77], v[58:59]
	v_pk_fma_f32 v[78:79], v[52:53], v[78:79], v[52:53]
	v_pk_fma_f32 v[80:81], v[54:55], v[80:81], v[54:55]
	v_pk_fma_f32 v[82:83], v[48:49], v[82:83], v[48:49]
	v_pk_fma_f32 v[84:85], v[50:51], v[84:85], v[50:51]
	v_pk_mul_f32 v[64:65], v[64:65], v[192:193] op_sel_hi:[1,0]
	v_pk_mul_f32 v[68:69], v[68:69], v[192:193] op_sel_hi:[1,0]
	v_pk_mul_f32 v[74:75], v[74:75], v[192:193] op_sel_hi:[1,0]
	v_pk_mul_f32 v[76:77], v[76:77], v[192:193] op_sel_hi:[1,0]
	v_pk_mul_f32 v[78:79], v[78:79], v[192:193] op_sel_hi:[1,0]
	v_pk_mul_f32 v[80:81], v[80:81], v[192:193] op_sel_hi:[1,0]
	v_pk_mul_f32 v[82:83], v[82:83], v[192:193] op_sel_hi:[1,0]
	v_pk_mul_f32 v[84:85], v[84:85], v[192:193] op_sel_hi:[1,0]
	v_pk_mul_f32 v[64:65], v[64:65], v[194:195] op_sel_hi:[1,0]
	v_pk_mul_f32 v[68:69], v[68:69], v[194:195] op_sel_hi:[1,0]
	v_pk_mul_f32 v[74:75], v[74:75], v[194:195] op_sel_hi:[1,0]
	v_pk_mul_f32 v[76:77], v[76:77], v[194:195] op_sel_hi:[1,0]
	v_pk_mul_f32 v[78:79], v[78:79], v[194:195] op_sel_hi:[1,0]
	v_pk_mul_f32 v[80:81], v[80:81], v[194:195] op_sel_hi:[1,0]
	v_pk_mul_f32 v[82:83], v[82:83], v[194:195] op_sel_hi:[1,0]
	v_pk_mul_f32 v[84:85], v[84:85], v[194:195] op_sel_hi:[1,0]
	v_exp_f32_e32 v64, v64
	v_exp_f32_e32 v65, v65
	v_exp_f32_e32 v68, v68
	v_exp_f32_e32 v69, v69
	v_exp_f32_e32 v74, v74
	v_exp_f32_e32 v75, v75
	v_exp_f32_e32 v76, v76
	v_exp_f32_e32 v77, v77
	v_exp_f32_e32 v78, v78
	v_exp_f32_e32 v79, v79
	v_exp_f32_e32 v80, v80
	v_exp_f32_e32 v81, v81
	v_exp_f32_e32 v82, v82
	v_exp_f32_e32 v83, v83
	v_exp_f32_e32 v84, v84
	v_exp_f32_e32 v85, v85
	v_pk_add_f32 v[64:65], v[64:65], 1.0 op_sel_hi:[1,0]
	v_pk_add_f32 v[68:69], v[68:69], 1.0 op_sel_hi:[1,0]
	v_pk_add_f32 v[74:75], v[74:75], 1.0 op_sel_hi:[1,0]
	v_pk_add_f32 v[76:77], v[76:77], 1.0 op_sel_hi:[1,0]
	v_pk_add_f32 v[78:79], v[78:79], 1.0 op_sel_hi:[1,0]
	v_pk_add_f32 v[80:81], v[80:81], 1.0 op_sel_hi:[1,0]
	v_pk_add_f32 v[82:83], v[82:83], 1.0 op_sel_hi:[1,0]
	v_pk_add_f32 v[84:85], v[84:85], 1.0 op_sel_hi:[1,0]
	v_rcp_f32_e32 v64, v64
	v_rcp_f32_e32 v65, v65
	v_rcp_f32_e32 v68, v68
	v_rcp_f32_e32 v69, v69
	v_rcp_f32_e32 v74, v74
	v_rcp_f32_e32 v75, v75
	v_rcp_f32_e32 v76, v76
	v_rcp_f32_e32 v77, v77
	v_rcp_f32_e32 v78, v78
	v_rcp_f32_e32 v79, v79
	v_rcp_f32_e32 v80, v80
	v_rcp_f32_e32 v81, v81
	v_rcp_f32_e32 v82, v82
	v_rcp_f32_e32 v83, v83
	v_rcp_f32_e32 v84, v84
	v_rcp_f32_e32 v85, v85
	v_pk_mul_f32 v[64:65], v[60:61], v[64:65]
	v_pk_mul_f32 v[68:69], v[62:63], v[68:69]
	v_pk_mul_f32 v[74:75], v[56:57], v[74:75]
	v_pk_mul_f32 v[76:77], v[58:59], v[76:77]
	v_pk_mul_f32 v[78:79], v[52:53], v[78:79]
	v_pk_mul_f32 v[80:81], v[54:55], v[80:81]
	v_pk_mul_f32 v[82:83], v[48:49], v[82:83]
	v_pk_mul_f32 v[84:85], v[50:51], v[84:85]
	v_pk_mul_f32 v[66:67], v[64:65], v[64:65]
	v_pk_mul_f32 v[70:71], v[68:69], v[68:69]
	v_add_f32_e32 v66, v66, v67
	v_add_f32_e32 v66, v70, v66
	v_pk_mul_f32 v[86:87], v[74:75], v[74:75]
	v_add_f32_e32 v66, v71, v66
	v_add_f32_e32 v66, v86, v66
	v_pk_mul_f32 v[88:89], v[76:77], v[76:77]
	v_add_f32_e32 v66, v87, v66
	v_add_f32_e32 v66, v88, v66
	v_pk_mul_f32 v[90:91], v[78:79], v[78:79]
	v_add_f32_e32 v66, v89, v66
	v_add_f32_e32 v66, v66, v90
	v_pk_mul_f32 v[92:93], v[80:81], v[80:81]
	v_add_f32_e32 v66, v91, v66
	v_add_f32_e32 v66, v92, v66
	v_pk_mul_f32 v[94:95], v[82:83], v[82:83]
	v_add_f32_e32 v66, v93, v66
	v_add_f32_e32 v66, v94, v66
	v_pk_mul_f32 v[96:97], v[84:85], v[84:85]
	v_add_f32_e32 v66, v95, v66
	v_add_f32_e32 v66, v96, v66
	v_add_f32_e32 v66, v97, v66
	ds_bpermute_b32 v67, v229, v66
	v_lshl_add_u64 v[96:97], v[140:141], 2, s[18:19]
	v_ashrrev_i32_e32 v73, 31, v72
	v_lshlrev_b64 v[90:91], 10, v[72:73]
	v_lshlrev_b32_e32 v88, 9, v72
	s_waitcnt lgkmcnt(0)
	v_add_f32_e32 v66, v66, v67
	ds_bpermute_b32 v67, v230, v66
	v_mov_b32_e32 v89, v141
	s_waitcnt lgkmcnt(0)
	v_add_f32_e32 v66, v66, v67
	v_fmamk_f32 v66, v66, 0x3c800000, v188
	v_cmp_gt_f32_e32 vcc, s13, v66
	v_mul_f32_e32 v67, 0x4b800000, v66
	s_nop 0
	v_cndmask_b32_e32 v66, v66, v67, vcc
	v_rsq_f32_e32 v66, v66
	s_nop 0
	v_mul_f32_e32 v67, 0x45800000, v66
	v_cndmask_b32_e32 v86, v66, v67, vcc
	v_pk_mul_f32 v[92:93], v[64:65], v[86:87] op_sel_hi:[1,0]
	v_pk_mul_f32 v[94:95], v[68:69], v[86:87] op_sel_hi:[1,0]
	v_mov_b64_e32 v[64:65], v[208:209]
	v_mov_b64_e32 v[66:67], v[210:211]
	v_mov_b64_e32 v[68:69], v[204:205]
	v_mov_b64_e32 v[70:71], v[206:207]
	v_pk_mul_f32 v[74:75], v[74:75], v[86:87] op_sel_hi:[1,0]
	v_pk_mul_f32 v[76:77], v[76:77], v[86:87] op_sel_hi:[1,0]
	v_pk_mul_f32 v[64:65], v[64:65], v[74:75]
	v_lshl_add_u64 v[74:75], s[46:47], 0, v[90:91]
	v_pk_mul_f32 v[70:71], v[70:71], v[94:95]
	v_pk_mul_f32 v[68:69], v[68:69], v[92:93]
	v_pk_mul_f32 v[66:67], v[66:67], v[76:77]
	v_lshl_add_u64 v[76:77], v[140:141], 1, v[74:75]
	v_lshl_add_u64 v[74:75], v[88:89], 2, s[56:57]
	v_cvt_pk_bf16_f32 v90, v68, v69
	v_cvt_pk_bf16_f32 v91, v70, v71
	v_cvt_pk_bf16_f32 v92, v64, v65
	v_cvt_pk_bf16_f32 v93, v66, v67
	global_store_dwordx4 v[76:77], v[90:93], off
	s_and_saveexec_b64 s[0:1], s[10:11]
	s_cbranch_execz .LBB0_298
	v_lshl_add_u64 v[88:89], v[140:141], 2, v[74:75]
	v_lshl_add_u64 v[90:91], v[88:89], 0, s[70:71]
	v_add_co_u32_e32 v88, vcc, 0x2108000, v88
	s_nop 1
	v_addc_co_u32_e32 v89, vcc, 0, v89, vcc
	global_store_dwordx4 v[88:89], v[68:71], off
	global_store_dwordx4 v[90:91], v[64:67], off offset:16
; __device__ __forceinline__ void st_bf16x8(bf16_t* p, const f32x4 a, const f32x4 b) { uint4 o; o.x = cvt_pk_bf16(a[0], a[1]); o.y = cvt_pk_bf16(a[2], a[3]); o.z = cvt_pk_bf16(b[0], b[1]); o.w = cvt_pk_bf16(b[2], b[3]); *(uint4*)p = o; }
;     __device__ __forceinline__ void row(const f32x4 (&a)[2][2], int row, int pn, int wc, int fq) const {
;     ...
;             for (int bj = 0; bj < 2; ++bj) { const int d = head * 64 + bj * 32 + 8 * fq;
;                 const f32x4 v0 = g[bj][0] * rs * *(const f32x4*)(g_v + d), v1 = g[bj][1] * rs * *(const f32x4*)(g_v + d + 4);
;                 st_bf16x8(pV + (size_t)row * 512 + d, v0, v1);
;                 if (row >= NP && row < NTOK) { float* o = out + O_VS + (size_t)(row - NP) * 512 + d; *(f32x4*)o = v0; *(f32x4*)(o + 4) = v1; } }
.LBB0_298:
	s_or_b64 exec, exec, s[0:1]
	v_mov_b64_e32 v[64:65], v[212:213]
	v_mov_b64_e32 v[66:67], v[214:215]
	v_mov_b64_e32 v[68:69], v[216:217]
	v_mov_b64_e32 v[70:71], v[218:219]
	v_mov_b32_e32 v87, v86
	v_mov_b32_e32 v88, v86
	v_mov_b32_e32 v89, v86
	v_pk_mul_f32 v[78:79], v[78:79], v[86:87]
	v_pk_mul_f32 v[80:81], v[80:81], v[88:89]
	v_pk_mul_f32 v[82:83], v[82:83], v[86:87]
	v_pk_mul_f32 v[84:85], v[84:85], v[88:89]
	v_pk_mul_f32 v[66:67], v[80:81], v[66:67]
	v_pk_mul_f32 v[64:65], v[78:79], v[64:65]
	v_pk_mul_f32 v[70:71], v[84:85], v[70:71]
	v_pk_mul_f32 v[68:69], v[82:83], v[68:69]
	v_cvt_pk_bf16_f32 v78, v64, v65
	v_cvt_pk_bf16_f32 v79, v66, v67
	v_cvt_pk_bf16_f32 v81, v70, v71
	s_nop 0
	v_cvt_pk_bf16_f32 v80, v68, v69
	global_store_dwordx4 v[76:77], v[78:81], off offset:64
	s_and_saveexec_b64 s[0:1], s[10:11]
	s_cbranch_execz .LBB0_300
	v_lshl_add_u64 v[74:75], v[152:153], 2, v[74:75]
	v_lshl_add_u64 v[76:77], v[74:75], 0, s[70:71]
	v_add_co_u32_e32 v74, vcc, 0x2108000, v74
	s_nop 1
	v_addc_co_u32_e32 v75, vcc, 0, v75, vcc
	global_store_dwordx4 v[74:75], v[64:67], off
	global_store_dwordx4 v[76:77], v[68:71], off offset:16

; __device__ __forceinline__ float gelu_tanh(float x) { const float u = 1.5957691216f * (x + 0.044715f * x * x * x); return x * __builtin_amdgcn_rcpf(1.f + __expf(-u)); }
; __device__ __forceinline__ void st_bf16x8(bf16_t* p, const f32x4 a, const f32x4 b) { uint4 o; o.x = cvt_pk_bf16(a[0], a[1]); o.y = cvt_pk_bf16(a[2], a[3]); o.z = cvt_pk_bf16(b[0], b[1]); o.w = cvt_pk_bf16(b[2], b[3]); *(uint4*)p = o; }
;     __device__ __forceinline__ void row(const f32x4 (&a)[2][2], int row, int pn, int wc, int fq) const {
;     ...
;             const int head = (pn - 2) * 4 + wc;
;             f32x4 g[2][2]; float ss = 0.f;
; #pragma unroll
;             for (int bj = 0; bj < 2; ++bj)
; #pragma unroll
;                 for (int n = 0; n < 2; ++n)
; #pragma unroll
;                     for (int j = 0; j < 4; ++j) { const float t = gelu_tanh(a[bj][n][j]); g[bj][n][j] = t; ss += t * t; }
;             ss += __shfl_xor(ss, 16); ss += __shfl_xor(ss, 32);
;             const float rs = rsqrtf(ss * (1.f / 64.f) + EPS);
; #pragma unroll
;             for (int bj = 0; bj < 2; ++bj) { const int d = head * 64 + bj * 32 + 8 * fq;
;                 const f32x4 v0 = g[bj][0] * rs * *(const f32x4*)(g_v + d), v1 = g[bj][1] * rs * *(const f32x4*)(g_v + d + 4);
;                 st_bf16x8(pV + (size_t)row * 512 + d, v0, v1);
;                 if (row >= NP && row < NTOK) { float* o = out + O_VS + (size_t)(row - NP) * 512 + d; *(f32x4*)o = v0; *(f32x4*)(o + 4) = v1; } }
.LBB0_311:
	s_andn2_b64 vcc, exec, s[0:1]
	s_cbranch_vccnz .LBB0_317
	v_mov_b32_e32 v190, 0x3d372713
	v_mov_b32_e32 v192, 0xbfcc422a
	v_mov_b32_e32 v194, 0x3fb8aa3b
	v_pk_mul_f32 v[48:49], v[44:45], v[190:191] op_sel_hi:[1,0]
	v_pk_mul_f32 v[52:53], v[46:47], v[190:191] op_sel_hi:[1,0]
	v_pk_mul_f32 v[58:59], v[40:41], v[190:191] op_sel_hi:[1,0]
	v_pk_mul_f32 v[60:61], v[42:43], v[190:191] op_sel_hi:[1,0]
	v_pk_mul_f32 v[62:63], v[36:37], v[190:191] op_sel_hi:[1,0]
	v_pk_mul_f32 v[64:65], v[38:39], v[190:191] op_sel_hi:[1,0]
	v_pk_mul_f32 v[66:67], v[32:33], v[190:191] op_sel_hi:[1,0]
	v_pk_mul_f32 v[68:69], v[34:35], v[190:191] op_sel_hi:[1,0]
	v_pk_mul_f32 v[48:49], v[44:45], v[48:49]
	v_pk_mul_f32 v[52:53], v[46:47], v[52:53]
	v_pk_mul_f32 v[58:59], v[40:41], v[58:59]
	v_pk_mul_f32 v[60:61], v[42:43], v[60:61]
	v_pk_mul_f32 v[62:63], v[36:37], v[62:63]
	v_pk_mul_f32 v[64:65], v[38:39], v[64:65]
	v_pk_mul_f32 v[66:67], v[32:33], v[66:67]
	v_pk_mul_f32 v[68:69], v[34:35], v[68:69]
	v_pk_fma_f32 v[48:49], v[44:45], v[48:49], v[44:45]
	v_pk_fma_f32 v[52:53], v[46:47], v[52:53], v[46:47]
	v_pk_fma_f32 v[58:59], v[40:41], v[58:59], v[40:41]
	v_pk_fma_f32 v[60:61], v[42:43], v[60:61], v[42:43]
	v_pk_fma_f32 v[62:63], v[36:37], v[62:63], v[36:37]
	v_pk_fma_f32 v[64:65], v[38:39], v[64:65], v[38:39]
	v_pk_fma_f32 v[66:67], v[32:33], v[66:67], v[32:33]
	v_pk_fma_f32 v[68:69], v[34:35], v[68:69], v[34:35]
	v_pk_mul_f32 v[48:49], v[48:49], v[192:193] op_sel_hi:[1,0]
	v_pk_mul_f32 v[52:53], v[52:53], v[192:193] op_sel_hi:[1,0]
	v_pk_mul_f32 v[58:59], v[58:59], v[192:193] op_sel_hi:[1,0]
	v_pk_mul_f32 v[60:61], v[60:61], v[192:193] op_sel_hi:[1,0]
	v_pk_mul_f32 v[62:63], v[62:63], v[192:193] op_sel_hi:[1,0]
	v_pk_mul_f32 v[64:65], v[64:65], v[192:193] op_sel_hi:[1,0]
	v_pk_mul_f32 v[66:67], v[66:67], v[192:193] op_sel_hi:[1,0]
	v_pk_mul_f32 v[68:69], v[68:69], v[192:193] op_sel_hi:[1,0]
	v_pk_mul_f32 v[48:49], v[48:49], v[194:195] op_sel_hi:[1,0]
	v_pk_mul_f32 v[52:53], v[52:53], v[194:195] op_sel_hi:[1,0]
	v_pk_mul_f32 v[58:59], v[58:59], v[194:195] op_sel_hi:[1,0]
	v_pk_mul_f32 v[60:61], v[60:61], v[194:195] op_sel_hi:[1,0]
	v_pk_mul_f32 v[62:63], v[62:63], v[194:195] op_sel_hi:[1,0]
	v_pk_mul_f32 v[64:65], v[64:65], v[194:195] op_sel_hi:[1,0]
	v_pk_mul_f32 v[66:67], v[66:67], v[194:195] op_sel_hi:[1,0]
	v_pk_mul_f32 v[68:69], v[68:69], v[194:195] op_sel_hi:[1,0]
	v_exp_f32_e32 v48, v48
	v_exp_f32_e32 v49, v49
	v_exp_f32_e32 v52, v52
	v_exp_f32_e32 v53, v53
	v_exp_f32_e32 v58, v58
	v_exp_f32_e32 v59, v59
	v_exp_f32_e32 v60, v60
	v_exp_f32_e32 v61, v61
	v_exp_f32_e32 v62, v62
	v_exp_f32_e32 v63, v63
	v_exp_f32_e32 v64, v64
	v_exp_f32_e32 v65, v65
	v_exp_f32_e32 v66, v66
	v_exp_f32_e32 v67, v67
	v_exp_f32_e32 v68, v68
	v_exp_f32_e32 v69, v69
	v_pk_add_f32 v[48:49], v[48:49], 1.0 op_sel_hi:[1,0]
	v_pk_add_f32 v[52:53], v[52:53], 1.0 op_sel_hi:[1,0]
	v_pk_add_f32 v[58:59], v[58:59], 1.0 op_sel_hi:[1,0]
	v_pk_add_f32 v[60:61], v[60:61], 1.0 op_sel_hi:[1,0]
	v_pk_add_f32 v[62:63], v[62:63], 1.0 op_sel_hi:[1,0]
	v_pk_add_f32 v[64:65], v[64:65], 1.0 op_sel_hi:[1,0]
	v_pk_add_f32 v[66:67], v[66:67], 1.0 op_sel_hi:[1,0]
	v_pk_add_f32 v[68:69], v[68:69], 1.0 op_sel_hi:[1,0]
	v_rcp_f32_e32 v48, v48
	v_rcp_f32_e32 v49, v49
	v_rcp_f32_e32 v52, v52
	v_rcp_f32_e32 v53, v53
	v_rcp_f32_e32 v58, v58
	v_rcp_f32_e32 v59, v59
	v_rcp_f32_e32 v60, v60
	v_rcp_f32_e32 v61, v61
	v_rcp_f32_e32 v62, v62
	v_rcp_f32_e32 v63, v63
	v_rcp_f32_e32 v64, v64
	v_rcp_f32_e32 v65, v65
	v_rcp_f32_e32 v66, v66
	v_rcp_f32_e32 v67, v67
	v_rcp_f32_e32 v68, v68
	v_rcp_f32_e32 v69, v69
	v_pk_mul_f32 v[48:49], v[44:45], v[48:49]
	v_pk_mul_f32 v[52:53], v[46:47], v[52:53]
	v_pk_mul_f32 v[58:59], v[40:41], v[58:59]
	v_pk_mul_f32 v[60:61], v[42:43], v[60:61]
	v_pk_mul_f32 v[62:63], v[36:37], v[62:63]
	v_pk_mul_f32 v[64:65], v[38:39], v[64:65]
	v_pk_mul_f32 v[66:67], v[32:33], v[66:67]
	v_pk_mul_f32 v[68:69], v[34:35], v[68:69]
	v_pk_mul_f32 v[50:51], v[48:49], v[48:49]
	v_pk_mul_f32 v[54:55], v[52:53], v[52:53]
	v_add_f32_e32 v50, v50, v51
	v_add_f32_e32 v50, v54, v50
	v_pk_mul_f32 v[70:71], v[58:59], v[58:59]
	v_add_f32_e32 v50, v55, v50
	v_add_f32_e32 v50, v70, v50
	v_pk_mul_f32 v[74:75], v[60:61], v[60:61]
	v_add_f32_e32 v50, v71, v50
	v_add_f32_e32 v50, v74, v50
	v_pk_mul_f32 v[76:77], v[62:63], v[62:63]
	v_add_f32_e32 v50, v75, v50
	v_add_f32_e32 v50, v50, v76
	v_pk_mul_f32 v[78:79], v[64:65], v[64:65]
	v_add_f32_e32 v50, v77, v50
	v_add_f32_e32 v50, v78, v50
	v_pk_mul_f32 v[80:81], v[66:67], v[66:67]
	v_add_f32_e32 v50, v79, v50
	v_add_f32_e32 v50, v80, v50
	v_pk_mul_f32 v[82:83], v[68:69], v[68:69]
	v_add_f32_e32 v50, v81, v50
	v_add_f32_e32 v50, v82, v50
	v_add_f32_e32 v50, v83, v50
	ds_bpermute_b32 v51, v229, v50
	v_lshl_add_u64 v[82:83], v[140:141], 2, s[18:19]
	v_ashrrev_i32_e32 v57, 31, v56
	v_lshlrev_b64 v[76:77], 10, v[56:57]
	v_lshlrev_b32_e32 v74, 9, v56
	s_waitcnt lgkmcnt(0)
	v_add_f32_e32 v50, v50, v51
	ds_bpermute_b32 v51, v230, v50
	v_mov_b32_e32 v75, v141
	s_waitcnt lgkmcnt(0)
	v_add_f32_e32 v50, v50, v51
	v_fmamk_f32 v50, v50, 0x3c800000, v188
	v_cmp_gt_f32_e32 vcc, s13, v50
	v_mul_f32_e32 v51, 0x4b800000, v50
	s_nop 0
	v_cndmask_b32_e32 v50, v50, v51, vcc
	v_rsq_f32_e32 v50, v50
	s_nop 0
	v_mul_f32_e32 v51, 0x45800000, v50
	v_cndmask_b32_e32 v70, v50, v51, vcc
	v_pk_mul_f32 v[78:79], v[48:49], v[70:71] op_sel_hi:[1,0]
	v_pk_mul_f32 v[80:81], v[52:53], v[70:71] op_sel_hi:[1,0]
	v_mov_b64_e32 v[48:49], v[208:209]
	v_mov_b64_e32 v[50:51], v[210:211]
	v_mov_b64_e32 v[52:53], v[204:205]
	v_mov_b64_e32 v[54:55], v[206:207]
	v_pk_mul_f32 v[58:59], v[58:59], v[70:71] op_sel_hi:[1,0]
	v_pk_mul_f32 v[60:61], v[60:61], v[70:71] op_sel_hi:[1,0]
	v_pk_mul_f32 v[48:49], v[48:49], v[58:59]
	v_lshl_add_u64 v[58:59], s[46:47], 0, v[76:77]
	v_pk_mul_f32 v[54:55], v[54:55], v[80:81]
	v_pk_mul_f32 v[52:53], v[52:53], v[78:79]
	v_pk_mul_f32 v[50:51], v[50:51], v[60:61]
	v_lshl_add_u64 v[60:61], v[140:141], 1, v[58:59]
	v_lshl_add_u64 v[58:59], v[74:75], 2, s[56:57]
	v_cvt_pk_bf16_f32 v76, v52, v53
	v_cvt_pk_bf16_f32 v77, v54, v55
	v_cvt_pk_bf16_f32 v78, v48, v49
	v_cvt_pk_bf16_f32 v79, v50, v51
	global_store_dwordx4 v[60:61], v[76:79], off
	s_and_saveexec_b64 s[0:1], s[10:11]
	s_cbranch_execz .LBB0_314
	v_lshl_add_u64 v[74:75], v[140:141], 2, v[58:59]
	v_lshl_add_u64 v[76:77], v[74:75], 0, s[70:71]
	v_add_co_u32_e32 v74, vcc, 0x2108000, v74
	s_nop 1
	v_addc_co_u32_e32 v75, vcc, 0, v75, vcc
	global_store_dwordx4 v[74:75], v[52:55], off
	global_store_dwordx4 v[76:77], v[48:51], off offset:16
; __device__ __forceinline__ void st_bf16x8(bf16_t* p, const f32x4 a, const f32x4 b) { uint4 o; o.x = cvt_pk_bf16(a[0], a[1]); o.y = cvt_pk_bf16(a[2], a[3]); o.z = cvt_pk_bf16(b[0], b[1]); o.w = cvt_pk_bf16(b[2], b[3]); *(uint4*)p = o; }
;     __device__ __forceinline__ void row(const f32x4 (&a)[2][2], int row, int pn, int wc, int fq) const {
;     ...
;             for (int bj = 0; bj < 2; ++bj) { const int d = head * 64 + bj * 32 + 8 * fq;
;                 const f32x4 v0 = g[bj][0] * rs * *(const f32x4*)(g_v + d), v1 = g[bj][1] * rs * *(const f32x4*)(g_v + d + 4);
;                 st_bf16x8(pV + (size_t)row * 512 + d, v0, v1);
;                 if (row >= NP && row < NTOK) { float* o = out + O_VS + (size_t)(row - NP) * 512 + d; *(f32x4*)o = v0; *(f32x4*)(o + 4) = v1; } }
.LBB0_314:
	s_or_b64 exec, exec, s[0:1]
	v_mov_b64_e32 v[48:49], v[212:213]
	v_mov_b64_e32 v[50:51], v[214:215]
	v_mov_b64_e32 v[52:53], v[216:217]
	v_mov_b64_e32 v[54:55], v[218:219]
	v_mov_b32_e32 v71, v70
	v_mov_b32_e32 v74, v70
	v_mov_b32_e32 v75, v70
	v_pk_mul_f32 v[62:63], v[62:63], v[70:71]
	v_pk_mul_f32 v[64:65], v[64:65], v[74:75]
	v_pk_mul_f32 v[66:67], v[66:67], v[70:71]
	v_pk_mul_f32 v[68:69], v[68:69], v[74:75]
	v_pk_mul_f32 v[50:51], v[64:65], v[50:51]
	v_pk_mul_f32 v[48:49], v[62:63], v[48:49]
	v_pk_mul_f32 v[54:55], v[68:69], v[54:55]
	v_pk_mul_f32 v[52:53], v[66:67], v[52:53]
	v_cvt_pk_bf16_f32 v62, v48, v49
	v_cvt_pk_bf16_f32 v63, v50, v51
	v_cvt_pk_bf16_f32 v65, v54, v55
	s_nop 0
	v_cvt_pk_bf16_f32 v64, v52, v53
	global_store_dwordx4 v[60:61], v[62:65], off offset:64
	s_and_saveexec_b64 s[0:1], s[10:11]
	s_cbranch_execz .LBB0_316
	v_lshl_add_u64 v[58:59], v[152:153], 2, v[58:59]
	v_lshl_add_u64 v[60:61], v[58:59], 0, s[70:71]
	v_add_co_u32_e32 v58, vcc, 0x2108000, v58
	s_nop 1
	v_addc_co_u32_e32 v59, vcc, 0, v59, vcc
	global_store_dwordx4 v[58:59], v[48:51], off
	global_store_dwordx4 v[60:61], v[52:55], off offset:16

; __device__ __forceinline__ float gelu_tanh(float x) { const float u = 1.5957691216f * (x + 0.044715f * x * x * x); return x * __builtin_amdgcn_rcpf(1.f + __expf(-u)); }
; __device__ __forceinline__ void st_bf16x8(bf16_t* p, const f32x4 a, const f32x4 b) { uint4 o; o.x = cvt_pk_bf16(a[0], a[1]); o.y = cvt_pk_bf16(a[2], a[3]); o.z = cvt_pk_bf16(b[0], b[1]); o.w = cvt_pk_bf16(b[2], b[3]); *(uint4*)p = o; }
;     __device__ __forceinline__ void row(const f32x4 (&a)[2][2], int row, int pn, int wc, int fq) const {
;     ...
;             const int head = (pn - 2) * 4 + wc;
;             f32x4 g[2][2]; float ss = 0.f;
; #pragma unroll
;             for (int bj = 0; bj < 2; ++bj)
; #pragma unroll
;                 for (int n = 0; n < 2; ++n)
; #pragma unroll
;                     for (int j = 0; j < 4; ++j) { const float t = gelu_tanh(a[bj][n][j]); g[bj][n][j] = t; ss += t * t; }
;             ss += __shfl_xor(ss, 16); ss += __shfl_xor(ss, 32);
;             const float rs = rsqrtf(ss * (1.f / 64.f) + EPS);
; #pragma unroll
;             for (int bj = 0; bj < 2; ++bj) { const int d = head * 64 + bj * 32 + 8 * fq;
;                 const f32x4 v0 = g[bj][0] * rs * *(const f32x4*)(g_v + d), v1 = g[bj][1] * rs * *(const f32x4*)(g_v + d + 4);
;                 st_bf16x8(pV + (size_t)row * 512 + d, v0, v1);
;                 if (row >= NP && row < NTOK) { float* o = out + O_VS + (size_t)(row - NP) * 512 + d; *(f32x4*)o = v0; *(f32x4*)(o + 4) = v1; } }
.LBB0_327:
	s_andn2_b64 vcc, exec, s[0:1]
	s_cbranch_vccnz .LBB0_333
	v_mov_b32_e32 v190, 0x3d372713
	v_mov_b32_e32 v192, 0xbfcc422a
	v_mov_b32_e32 v194, 0x3fb8aa3b
	v_pk_mul_f32 v[32:33], v[28:29], v[190:191] op_sel_hi:[1,0]
	v_pk_mul_f32 v[36:37], v[30:31], v[190:191] op_sel_hi:[1,0]
	v_pk_mul_f32 v[42:43], v[24:25], v[190:191] op_sel_hi:[1,0]
	v_pk_mul_f32 v[44:45], v[26:27], v[190:191] op_sel_hi:[1,0]
	v_pk_mul_f32 v[46:47], v[20:21], v[190:191] op_sel_hi:[1,0]
	v_pk_mul_f32 v[48:49], v[22:23], v[190:191] op_sel_hi:[1,0]
	v_pk_mul_f32 v[50:51], v[16:17], v[190:191] op_sel_hi:[1,0]
	v_pk_mul_f32 v[52:53], v[18:19], v[190:191] op_sel_hi:[1,0]
	v_pk_mul_f32 v[32:33], v[28:29], v[32:33]
	v_pk_mul_f32 v[36:37], v[30:31], v[36:37]
	v_pk_mul_f32 v[42:43], v[24:25], v[42:43]
	v_pk_mul_f32 v[44:45], v[26:27], v[44:45]
	v_pk_mul_f32 v[46:47], v[20:21], v[46:47]
	v_pk_mul_f32 v[48:49], v[22:23], v[48:49]
	v_pk_mul_f32 v[50:51], v[16:17], v[50:51]
	v_pk_mul_f32 v[52:53], v[18:19], v[52:53]
	v_pk_fma_f32 v[32:33], v[28:29], v[32:33], v[28:29]
	v_pk_fma_f32 v[36:37], v[30:31], v[36:37], v[30:31]
	v_pk_fma_f32 v[42:43], v[24:25], v[42:43], v[24:25]
	v_pk_fma_f32 v[44:45], v[26:27], v[44:45], v[26:27]
	v_pk_fma_f32 v[46:47], v[20:21], v[46:47], v[20:21]
	v_pk_fma_f32 v[48:49], v[22:23], v[48:49], v[22:23]
	v_pk_fma_f32 v[50:51], v[16:17], v[50:51], v[16:17]
	v_pk_fma_f32 v[52:53], v[18:19], v[52:53], v[18:19]
	v_pk_mul_f32 v[32:33], v[32:33], v[192:193] op_sel_hi:[1,0]
	v_pk_mul_f32 v[36:37], v[36:37], v[192:193] op_sel_hi:[1,0]
	v_pk_mul_f32 v[42:43], v[42:43], v[192:193] op_sel_hi:[1,0]
	v_pk_mul_f32 v[44:45], v[44:45], v[192:193] op_sel_hi:[1,0]
	v_pk_mul_f32 v[46:47], v[46:47], v[192:193] op_sel_hi:[1,0]
	v_pk_mul_f32 v[48:49], v[48:49], v[192:193] op_sel_hi:[1,0]
	v_pk_mul_f32 v[50:51], v[50:51], v[192:193] op_sel_hi:[1,0]
	v_pk_mul_f32 v[52:53], v[52:53], v[192:193] op_sel_hi:[1,0]
	v_pk_mul_f32 v[32:33], v[32:33], v[194:195] op_sel_hi:[1,0]
	v_pk_mul_f32 v[36:37], v[36:37], v[194:195] op_sel_hi:[1,0]
	v_pk_mul_f32 v[42:43], v[42:43], v[194:195] op_sel_hi:[1,0]
	v_pk_mul_f32 v[44:45], v[44:45], v[194:195] op_sel_hi:[1,0]
	v_pk_mul_f32 v[46:47], v[46:47], v[194:195] op_sel_hi:[1,0]
	v_pk_mul_f32 v[48:49], v[48:49], v[194:195] op_sel_hi:[1,0]
	v_pk_mul_f32 v[50:51], v[50:51], v[194:195] op_sel_hi:[1,0]
	v_pk_mul_f32 v[52:53], v[52:53], v[194:195] op_sel_hi:[1,0]
	v_exp_f32_e32 v32, v32
	v_exp_f32_e32 v33, v33
	v_exp_f32_e32 v36, v36
	v_exp_f32_e32 v37, v37
	v_exp_f32_e32 v42, v42
	v_exp_f32_e32 v43, v43
	v_exp_f32_e32 v44, v44
	v_exp_f32_e32 v45, v45
	v_exp_f32_e32 v46, v46
	v_exp_f32_e32 v47, v47
	v_exp_f32_e32 v48, v48
	v_exp_f32_e32 v49, v49
	v_exp_f32_e32 v50, v50
	v_exp_f32_e32 v51, v51
	v_exp_f32_e32 v52, v52
	v_exp_f32_e32 v53, v53
	v_pk_add_f32 v[32:33], v[32:33], 1.0 op_sel_hi:[1,0]
	v_pk_add_f32 v[36:37], v[36:37], 1.0 op_sel_hi:[1,0]
	v_pk_add_f32 v[42:43], v[42:43], 1.0 op_sel_hi:[1,0]
	v_pk_add_f32 v[44:45], v[44:45], 1.0 op_sel_hi:[1,0]
	v_pk_add_f32 v[46:47], v[46:47], 1.0 op_sel_hi:[1,0]
	v_pk_add_f32 v[48:49], v[48:49], 1.0 op_sel_hi:[1,0]
	v_pk_add_f32 v[50:51], v[50:51], 1.0 op_sel_hi:[1,0]
	v_pk_add_f32 v[52:53], v[52:53], 1.0 op_sel_hi:[1,0]
	v_rcp_f32_e32 v32, v32
	v_rcp_f32_e32 v33, v33
	v_rcp_f32_e32 v36, v36
	v_rcp_f32_e32 v37, v37
	v_rcp_f32_e32 v42, v42
	v_rcp_f32_e32 v43, v43
	v_rcp_f32_e32 v44, v44
	v_rcp_f32_e32 v45, v45
	v_rcp_f32_e32 v46, v46
	v_rcp_f32_e32 v47, v47
	v_rcp_f32_e32 v48, v48
	v_rcp_f32_e32 v49, v49
	v_rcp_f32_e32 v50, v50
	v_rcp_f32_e32 v51, v51
	v_rcp_f32_e32 v52, v52
	v_rcp_f32_e32 v53, v53
	v_pk_mul_f32 v[32:33], v[28:29], v[32:33]
	v_pk_mul_f32 v[36:37], v[30:31], v[36:37]
	v_pk_mul_f32 v[42:43], v[24:25], v[42:43]
	v_pk_mul_f32 v[44:45], v[26:27], v[44:45]
	v_pk_mul_f32 v[46:47], v[20:21], v[46:47]
	v_pk_mul_f32 v[48:49], v[22:23], v[48:49]
	v_pk_mul_f32 v[50:51], v[16:17], v[50:51]
	v_pk_mul_f32 v[52:53], v[18:19], v[52:53]
	v_pk_mul_f32 v[34:35], v[32:33], v[32:33]
	v_pk_mul_f32 v[38:39], v[36:37], v[36:37]
	v_add_f32_e32 v34, v34, v35
	v_add_f32_e32 v34, v38, v34
	v_pk_mul_f32 v[54:55], v[42:43], v[42:43]
	v_add_f32_e32 v34, v39, v34
	v_add_f32_e32 v34, v54, v34
	v_pk_mul_f32 v[56:57], v[44:45], v[44:45]
	v_add_f32_e32 v34, v55, v34
	v_add_f32_e32 v34, v56, v34
	v_pk_mul_f32 v[58:59], v[46:47], v[46:47]
	v_add_f32_e32 v34, v57, v34
	v_add_f32_e32 v34, v34, v58
	v_pk_mul_f32 v[60:61], v[48:49], v[48:49]
	v_add_f32_e32 v34, v59, v34
	v_add_f32_e32 v34, v60, v34
	v_pk_mul_f32 v[62:63], v[50:51], v[50:51]
	v_add_f32_e32 v34, v61, v34
	v_add_f32_e32 v34, v62, v34
	v_pk_mul_f32 v[64:65], v[52:53], v[52:53]
	v_add_f32_e32 v34, v63, v34
	v_add_f32_e32 v34, v64, v34
	v_add_f32_e32 v34, v65, v34
	ds_bpermute_b32 v35, v229, v34
	v_lshl_add_u64 v[64:65], v[140:141], 2, s[18:19]
	v_ashrrev_i32_e32 v41, 31, v40
	v_lshlrev_b64 v[58:59], 10, v[40:41]
	v_lshlrev_b32_e32 v56, 9, v40
	s_waitcnt lgkmcnt(0)
	v_add_f32_e32 v34, v34, v35
	ds_bpermute_b32 v35, v230, v34
	v_mov_b32_e32 v57, v141
	s_waitcnt lgkmcnt(0)
	v_add_f32_e32 v34, v34, v35
	v_fmamk_f32 v34, v34, 0x3c800000, v188
	v_cmp_gt_f32_e32 vcc, s13, v34
	v_mul_f32_e32 v35, 0x4b800000, v34
	s_nop 0
	v_cndmask_b32_e32 v34, v34, v35, vcc
	v_rsq_f32_e32 v34, v34
	s_nop 0
	v_mul_f32_e32 v35, 0x45800000, v34
	v_cndmask_b32_e32 v54, v34, v35, vcc
	v_pk_mul_f32 v[60:61], v[32:33], v[54:55] op_sel_hi:[1,0]
	v_pk_mul_f32 v[62:63], v[36:37], v[54:55] op_sel_hi:[1,0]
	v_mov_b64_e32 v[32:33], v[208:209]
	v_mov_b64_e32 v[34:35], v[210:211]
	v_mov_b64_e32 v[36:37], v[204:205]
	v_mov_b64_e32 v[38:39], v[206:207]
	v_pk_mul_f32 v[42:43], v[42:43], v[54:55] op_sel_hi:[1,0]
	v_pk_mul_f32 v[44:45], v[44:45], v[54:55] op_sel_hi:[1,0]
	v_pk_mul_f32 v[32:33], v[32:33], v[42:43]
	v_lshl_add_u64 v[42:43], s[46:47], 0, v[58:59]
	v_pk_mul_f32 v[38:39], v[38:39], v[62:63]
	v_pk_mul_f32 v[36:37], v[36:37], v[60:61]
	v_pk_mul_f32 v[34:35], v[34:35], v[44:45]
	v_lshl_add_u64 v[44:45], v[140:141], 1, v[42:43]
	v_lshl_add_u64 v[42:43], v[56:57], 2, s[56:57]
	v_cvt_pk_bf16_f32 v58, v36, v37
	v_cvt_pk_bf16_f32 v59, v38, v39
	v_cvt_pk_bf16_f32 v60, v32, v33
	v_cvt_pk_bf16_f32 v61, v34, v35
	global_store_dwordx4 v[44:45], v[58:61], off
	s_and_saveexec_b64 s[0:1], s[10:11]
	s_cbranch_execz .LBB0_330
	v_lshl_add_u64 v[56:57], v[140:141], 2, v[42:43]
	v_lshl_add_u64 v[58:59], v[56:57], 0, s[70:71]
	v_add_co_u32_e32 v56, vcc, 0x2108000, v56
	s_nop 1
	v_addc_co_u32_e32 v57, vcc, 0, v57, vcc
	global_store_dwordx4 v[56:57], v[36:39], off
	global_store_dwordx4 v[58:59], v[32:35], off offset:16
; __device__ __forceinline__ void st_bf16x8(bf16_t* p, const f32x4 a, const f32x4 b) { uint4 o; o.x = cvt_pk_bf16(a[0], a[1]); o.y = cvt_pk_bf16(a[2], a[3]); o.z = cvt_pk_bf16(b[0], b[1]); o.w = cvt_pk_bf16(b[2], b[3]); *(uint4*)p = o; }
;     __device__ __forceinline__ void row(const f32x4 (&a)[2][2], int row, int pn, int wc, int fq) const {
;     ...
;             for (int bj = 0; bj < 2; ++bj) { const int d = head * 64 + bj * 32 + 8 * fq;
;                 const f32x4 v0 = g[bj][0] * rs * *(const f32x4*)(g_v + d), v1 = g[bj][1] * rs * *(const f32x4*)(g_v + d + 4);
;                 st_bf16x8(pV + (size_t)row * 512 + d, v0, v1);
;                 if (row >= NP && row < NTOK) { float* o = out + O_VS + (size_t)(row - NP) * 512 + d; *(f32x4*)o = v0; *(f32x4*)(o + 4) = v1; } }
.LBB0_330:
	s_or_b64 exec, exec, s[0:1]
	v_mov_b64_e32 v[32:33], v[212:213]
	v_mov_b64_e32 v[34:35], v[214:215]
	v_mov_b64_e32 v[36:37], v[216:217]
	v_mov_b64_e32 v[38:39], v[218:219]
	v_mov_b32_e32 v55, v54
	v_mov_b32_e32 v56, v54
	v_mov_b32_e32 v57, v54
	v_pk_mul_f32 v[46:47], v[46:47], v[54:55]
	v_pk_mul_f32 v[48:49], v[48:49], v[56:57]
	v_pk_mul_f32 v[50:51], v[50:51], v[54:55]
	v_pk_mul_f32 v[52:53], v[52:53], v[56:57]
	v_pk_mul_f32 v[34:35], v[48:49], v[34:35]
	v_pk_mul_f32 v[32:33], v[46:47], v[32:33]
	v_pk_mul_f32 v[38:39], v[52:53], v[38:39]
	v_pk_mul_f32 v[36:37], v[50:51], v[36:37]
	v_cvt_pk_bf16_f32 v46, v32, v33
	v_cvt_pk_bf16_f32 v47, v34, v35
	v_cvt_pk_bf16_f32 v49, v38, v39
	s_nop 0
	v_cvt_pk_bf16_f32 v48, v36, v37
	global_store_dwordx4 v[44:45], v[46:49], off offset:64
	s_and_saveexec_b64 s[0:1], s[10:11]
	s_cbranch_execz .LBB0_332
	v_lshl_add_u64 v[42:43], v[152:153], 2, v[42:43]
	v_lshl_add_u64 v[44:45], v[42:43], 0, s[70:71]
	v_add_co_u32_e32 v42, vcc, 0x2108000, v42
	s_nop 1
	v_addc_co_u32_e32 v43, vcc, 0, v43, vcc
	global_store_dwordx4 v[42:43], v[32:35], off
	global_store_dwordx4 v[44:45], v[36:39], off offset:16

; __device__ __forceinline__ float gelu_tanh(float x) { const float u = 1.5957691216f * (x + 0.044715f * x * x * x); return x * __builtin_amdgcn_rcpf(1.f + __expf(-u)); }
; __device__ __forceinline__ void st_bf16x8(bf16_t* p, const f32x4 a, const f32x4 b) { uint4 o; o.x = cvt_pk_bf16(a[0], a[1]); o.y = cvt_pk_bf16(a[2], a[3]); o.z = cvt_pk_bf16(b[0], b[1]); o.w = cvt_pk_bf16(b[2], b[3]); *(uint4*)p = o; }
;     __device__ __forceinline__ void row(const f32x4 (&a)[2][2], int row, int pn, int wc, int fq) const {
;     ...
;             const int head = (pn - 2) * 4 + wc;
;             f32x4 g[2][2]; float ss = 0.f;
; #pragma unroll
;             for (int bj = 0; bj < 2; ++bj)
; #pragma unroll
;                 for (int n = 0; n < 2; ++n)
; #pragma unroll
;                     for (int j = 0; j < 4; ++j) { const float t = gelu_tanh(a[bj][n][j]); g[bj][n][j] = t; ss += t * t; }
;             ss += __shfl_xor(ss, 16); ss += __shfl_xor(ss, 32);
;             const float rs = rsqrtf(ss * (1.f / 64.f) + EPS);
; #pragma unroll
;             for (int bj = 0; bj < 2; ++bj) { const int d = head * 64 + bj * 32 + 8 * fq;
;                 const f32x4 v0 = g[bj][0] * rs * *(const f32x4*)(g_v + d), v1 = g[bj][1] * rs * *(const f32x4*)(g_v + d + 4);
;                 st_bf16x8(pV + (size_t)row * 512 + d, v0, v1);
;                 if (row >= NP && row < NTOK) { float* o = out + O_VS + (size_t)(row - NP) * 512 + d; *(f32x4*)o = v0; *(f32x4*)(o + 4) = v1; } }
.LBB0_345:
	s_and_b64 vcc, exec, s[0:1]
	s_cbranch_vccz .LBB0_351
	v_mov_b32_e32 v190, 0x3d372713
	v_mov_b32_e32 v192, 0xbfcc422a
	v_mov_b32_e32 v194, 0x3fb8aa3b
	v_pk_mul_f32 v[16:17], v[12:13], v[190:191] op_sel_hi:[1,0]
	v_pk_mul_f32 v[20:21], v[14:15], v[190:191] op_sel_hi:[1,0]
	v_pk_mul_f32 v[26:27], v[8:9], v[190:191] op_sel_hi:[1,0]
	v_pk_mul_f32 v[28:29], v[10:11], v[190:191] op_sel_hi:[1,0]
	v_pk_mul_f32 v[30:31], v[4:5], v[190:191] op_sel_hi:[1,0]
	v_pk_mul_f32 v[32:33], v[6:7], v[190:191] op_sel_hi:[1,0]
	v_pk_mul_f32 v[34:35], v[0:1], v[190:191] op_sel_hi:[1,0]
	v_pk_mul_f32 v[36:37], v[2:3], v[190:191] op_sel_hi:[1,0]
	v_pk_mul_f32 v[16:17], v[12:13], v[16:17]
	v_pk_mul_f32 v[20:21], v[14:15], v[20:21]
	v_pk_mul_f32 v[26:27], v[8:9], v[26:27]
	v_pk_mul_f32 v[28:29], v[10:11], v[28:29]
	v_pk_mul_f32 v[30:31], v[4:5], v[30:31]
	v_pk_mul_f32 v[32:33], v[6:7], v[32:33]
	v_pk_mul_f32 v[34:35], v[0:1], v[34:35]
	v_pk_mul_f32 v[36:37], v[2:3], v[36:37]
	v_pk_fma_f32 v[16:17], v[12:13], v[16:17], v[12:13]
	v_pk_fma_f32 v[20:21], v[14:15], v[20:21], v[14:15]
	v_pk_fma_f32 v[26:27], v[8:9], v[26:27], v[8:9]
	v_pk_fma_f32 v[28:29], v[10:11], v[28:29], v[10:11]
	v_pk_fma_f32 v[30:31], v[4:5], v[30:31], v[4:5]
	v_pk_fma_f32 v[32:33], v[6:7], v[32:33], v[6:7]
	v_pk_fma_f32 v[34:35], v[0:1], v[34:35], v[0:1]
	v_pk_fma_f32 v[36:37], v[2:3], v[36:37], v[2:3]
	v_pk_mul_f32 v[16:17], v[16:17], v[192:193] op_sel_hi:[1,0]
	v_pk_mul_f32 v[20:21], v[20:21], v[192:193] op_sel_hi:[1,0]
	v_pk_mul_f32 v[26:27], v[26:27], v[192:193] op_sel_hi:[1,0]
	v_pk_mul_f32 v[28:29], v[28:29], v[192:193] op_sel_hi:[1,0]
	v_pk_mul_f32 v[30:31], v[30:31], v[192:193] op_sel_hi:[1,0]
	v_pk_mul_f32 v[32:33], v[32:33], v[192:193] op_sel_hi:[1,0]
	v_pk_mul_f32 v[34:35], v[34:35], v[192:193] op_sel_hi:[1,0]
	v_pk_mul_f32 v[36:37], v[36:37], v[192:193] op_sel_hi:[1,0]
	v_pk_mul_f32 v[16:17], v[16:17], v[194:195] op_sel_hi:[1,0]
	v_pk_mul_f32 v[20:21], v[20:21], v[194:195] op_sel_hi:[1,0]
	v_pk_mul_f32 v[26:27], v[26:27], v[194:195] op_sel_hi:[1,0]
	v_pk_mul_f32 v[28:29], v[28:29], v[194:195] op_sel_hi:[1,0]
	v_pk_mul_f32 v[30:31], v[30:31], v[194:195] op_sel_hi:[1,0]
	v_pk_mul_f32 v[32:33], v[32:33], v[194:195] op_sel_hi:[1,0]
	v_pk_mul_f32 v[34:35], v[34:35], v[194:195] op_sel_hi:[1,0]
	v_pk_mul_f32 v[36:37], v[36:37], v[194:195] op_sel_hi:[1,0]
	v_exp_f32_e32 v16, v16
	v_exp_f32_e32 v17, v17
	v_exp_f32_e32 v20, v20
	v_exp_f32_e32 v21, v21
	v_exp_f32_e32 v26, v26
	v_exp_f32_e32 v27, v27
	v_exp_f32_e32 v28, v28
	v_exp_f32_e32 v29, v29
	v_exp_f32_e32 v30, v30
	v_exp_f32_e32 v31, v31
	v_exp_f32_e32 v32, v32
	v_exp_f32_e32 v33, v33
	v_exp_f32_e32 v34, v34
	v_exp_f32_e32 v35, v35
	v_exp_f32_e32 v36, v36
	v_exp_f32_e32 v37, v37
	v_pk_add_f32 v[16:17], v[16:17], 1.0 op_sel_hi:[1,0]
	v_pk_add_f32 v[20:21], v[20:21], 1.0 op_sel_hi:[1,0]
	v_pk_add_f32 v[26:27], v[26:27], 1.0 op_sel_hi:[1,0]
	v_pk_add_f32 v[28:29], v[28:29], 1.0 op_sel_hi:[1,0]
	v_pk_add_f32 v[30:31], v[30:31], 1.0 op_sel_hi:[1,0]
	v_pk_add_f32 v[32:33], v[32:33], 1.0 op_sel_hi:[1,0]
	v_pk_add_f32 v[34:35], v[34:35], 1.0 op_sel_hi:[1,0]
	v_pk_add_f32 v[36:37], v[36:37], 1.0 op_sel_hi:[1,0]
	v_rcp_f32_e32 v16, v16
	v_rcp_f32_e32 v17, v17
	v_rcp_f32_e32 v20, v20
	v_rcp_f32_e32 v21, v21
	v_rcp_f32_e32 v26, v26
	v_rcp_f32_e32 v27, v27
	v_rcp_f32_e32 v28, v28
	v_rcp_f32_e32 v29, v29
	v_rcp_f32_e32 v30, v30
	v_rcp_f32_e32 v31, v31
	v_rcp_f32_e32 v32, v32
	v_rcp_f32_e32 v33, v33
	v_rcp_f32_e32 v34, v34
	v_rcp_f32_e32 v35, v35
	v_rcp_f32_e32 v36, v36
	v_rcp_f32_e32 v37, v37
	v_pk_mul_f32 v[16:17], v[12:13], v[16:17]
	v_pk_mul_f32 v[20:21], v[14:15], v[20:21]
	v_pk_mul_f32 v[26:27], v[8:9], v[26:27]
	v_pk_mul_f32 v[28:29], v[10:11], v[28:29]
	v_pk_mul_f32 v[30:31], v[4:5], v[30:31]
	v_pk_mul_f32 v[32:33], v[6:7], v[32:33]
	v_pk_mul_f32 v[34:35], v[0:1], v[34:35]
	v_pk_mul_f32 v[36:37], v[2:3], v[36:37]
	v_pk_mul_f32 v[18:19], v[16:17], v[16:17]
	v_pk_mul_f32 v[22:23], v[20:21], v[20:21]
	v_add_f32_e32 v18, v18, v19
	v_add_f32_e32 v18, v22, v18
	v_pk_mul_f32 v[38:39], v[26:27], v[26:27]
	v_add_f32_e32 v18, v23, v18
	v_add_f32_e32 v18, v38, v18
	v_pk_mul_f32 v[40:41], v[28:29], v[28:29]
	v_add_f32_e32 v18, v39, v18
	v_add_f32_e32 v18, v40, v18
	v_pk_mul_f32 v[42:43], v[30:31], v[30:31]
	v_add_f32_e32 v18, v41, v18
	v_add_f32_e32 v18, v18, v42
	v_pk_mul_f32 v[44:45], v[32:33], v[32:33]
	v_add_f32_e32 v18, v43, v18
	v_add_f32_e32 v18, v44, v18
	v_pk_mul_f32 v[46:47], v[34:35], v[34:35]
	v_add_f32_e32 v18, v45, v18
	v_add_f32_e32 v18, v46, v18
	v_pk_mul_f32 v[48:49], v[36:37], v[36:37]
	v_add_f32_e32 v18, v47, v18
	v_add_f32_e32 v18, v48, v18
	v_add_f32_e32 v18, v49, v18
	ds_bpermute_b32 v19, v229, v18
	v_lshl_add_u64 v[48:49], v[140:141], 2, s[18:19]
	v_ashrrev_i32_e32 v25, 31, v24
	v_lshlrev_b64 v[42:43], 10, v[24:25]
	v_lshlrev_b32_e32 v40, 9, v24
	s_waitcnt lgkmcnt(0)
	v_add_f32_e32 v18, v18, v19
	ds_bpermute_b32 v19, v230, v18
	v_mov_b32_e32 v41, v141
	s_waitcnt lgkmcnt(0)
	v_add_f32_e32 v18, v18, v19
	v_fmamk_f32 v18, v18, 0x3c800000, v188
	v_cmp_gt_f32_e32 vcc, s13, v18
	v_mul_f32_e32 v19, 0x4b800000, v18
	s_nop 0
	v_cndmask_b32_e32 v18, v18, v19, vcc
	v_rsq_f32_e32 v18, v18
	s_nop 0
	v_mul_f32_e32 v19, 0x45800000, v18
	v_cndmask_b32_e32 v38, v18, v19, vcc
	v_pk_mul_f32 v[44:45], v[16:17], v[38:39] op_sel_hi:[1,0]
	v_pk_mul_f32 v[46:47], v[20:21], v[38:39] op_sel_hi:[1,0]
	v_mov_b64_e32 v[16:17], v[208:209]
	v_mov_b64_e32 v[18:19], v[210:211]
	v_mov_b64_e32 v[20:21], v[204:205]
	v_mov_b64_e32 v[22:23], v[206:207]
	v_pk_mul_f32 v[26:27], v[26:27], v[38:39] op_sel_hi:[1,0]
	v_pk_mul_f32 v[28:29], v[28:29], v[38:39] op_sel_hi:[1,0]
	v_pk_mul_f32 v[16:17], v[16:17], v[26:27]
	v_lshl_add_u64 v[26:27], s[46:47], 0, v[42:43]
	v_pk_mul_f32 v[22:23], v[22:23], v[46:47]
	v_pk_mul_f32 v[20:21], v[20:21], v[44:45]
	v_pk_mul_f32 v[18:19], v[18:19], v[28:29]
	v_lshl_add_u64 v[28:29], v[140:141], 1, v[26:27]
	v_lshl_add_u64 v[26:27], v[40:41], 2, s[56:57]
	v_cvt_pk_bf16_f32 v42, v20, v21
	v_cvt_pk_bf16_f32 v43, v22, v23
	v_cvt_pk_bf16_f32 v44, v16, v17
	v_cvt_pk_bf16_f32 v45, v18, v19
	global_store_dwordx4 v[28:29], v[42:45], off
	s_and_saveexec_b64 s[0:1], s[10:11]
	s_cbranch_execz .LBB0_348
	v_lshl_add_u64 v[40:41], v[140:141], 2, v[26:27]
	v_lshl_add_u64 v[42:43], v[40:41], 0, s[70:71]
	v_add_co_u32_e32 v40, vcc, 0x2108000, v40
	s_nop 1
	v_addc_co_u32_e32 v41, vcc, 0, v41, vcc
	global_store_dwordx4 v[40:41], v[20:23], off
	global_store_dwordx4 v[42:43], v[16:19], off offset:16
; __device__ __forceinline__ void st_bf16x8(bf16_t* p, const f32x4 a, const f32x4 b) { uint4 o; o.x = cvt_pk_bf16(a[0], a[1]); o.y = cvt_pk_bf16(a[2], a[3]); o.z = cvt_pk_bf16(b[0], b[1]); o.w = cvt_pk_bf16(b[2], b[3]); *(uint4*)p = o; }
;     __device__ __forceinline__ void row(const f32x4 (&a)[2][2], int row, int pn, int wc, int fq) const {
;     ...
;             for (int bj = 0; bj < 2; ++bj) { const int d = head * 64 + bj * 32 + 8 * fq;
;                 const f32x4 v0 = g[bj][0] * rs * *(const f32x4*)(g_v + d), v1 = g[bj][1] * rs * *(const f32x4*)(g_v + d + 4);
;                 st_bf16x8(pV + (size_t)row * 512 + d, v0, v1);
;                 if (row >= NP && row < NTOK) { float* o = out + O_VS + (size_t)(row - NP) * 512 + d; *(f32x4*)o = v0; *(f32x4*)(o + 4) = v1; } }
.LBB0_348:
	s_or_b64 exec, exec, s[0:1]
	v_mov_b64_e32 v[16:17], v[212:213]
	v_mov_b64_e32 v[18:19], v[214:215]
	v_mov_b64_e32 v[20:21], v[216:217]
	v_mov_b64_e32 v[22:23], v[218:219]
	v_mov_b32_e32 v39, v38
	v_mov_b32_e32 v40, v38
	v_mov_b32_e32 v41, v38
	v_pk_mul_f32 v[30:31], v[30:31], v[38:39]
	v_pk_mul_f32 v[32:33], v[32:33], v[40:41]
	v_pk_mul_f32 v[34:35], v[34:35], v[38:39]
	v_pk_mul_f32 v[36:37], v[36:37], v[40:41]
	v_pk_mul_f32 v[18:19], v[32:33], v[18:19]
	v_pk_mul_f32 v[16:17], v[30:31], v[16:17]
	v_pk_mul_f32 v[22:23], v[36:37], v[22:23]
	v_pk_mul_f32 v[20:21], v[34:35], v[20:21]
	v_cvt_pk_bf16_f32 v30, v16, v17
	v_cvt_pk_bf16_f32 v31, v18, v19
	v_cvt_pk_bf16_f32 v33, v22, v23
	s_nop 0
	v_cvt_pk_bf16_f32 v32, v20, v21
	global_store_dwordx4 v[28:29], v[30:33], off offset:64
	s_and_saveexec_b64 s[0:1], s[10:11]
	s_cbranch_execz .LBB0_350
	v_lshl_add_u64 v[26:27], v[152:153], 2, v[26:27]
	v_lshl_add_u64 v[28:29], v[26:27], 0, s[70:71]
	v_add_co_u32_e32 v26, vcc, 0x2108000, v26
	s_nop 1
	v_addc_co_u32_e32 v27, vcc, 0, v27, vcc
	global_store_dwordx4 v[26:27], v[16:19], off
	global_store_dwordx4 v[28:29], v[20:23], off offset:16

; __global__ __launch_bounds__(512, 2) void fwd_megakernel(Params p) {
	.amdhsa_kernel _Z14fwd_megakernel6Params
		.amdhsa_group_segment_fixed_size 16
		.amdhsa_private_segment_fixed_size 0
		.amdhsa_kernarg_size 424
		.amdhsa_user_sgpr_count 2
		.amdhsa_user_sgpr_dispatch_ptr 0
		.amdhsa_user_sgpr_queue_ptr 0
		.amdhsa_user_sgpr_kernarg_segment_ptr 1
		.amdhsa_user_sgpr_dispatch_id 0
		.amdhsa_user_sgpr_kernarg_preload_length 0
		.amdhsa_user_sgpr_kernarg_preload_offset 0
		.amdhsa_user_sgpr_private_segment_size 0
		.amdhsa_uses_dynamic_stack 0
		.amdhsa_enable_private_segment 0
		.amdhsa_system_sgpr_workgroup_id_x 1
		.amdhsa_system_sgpr_workgroup_id_y 0
		.amdhsa_system_sgpr_workgroup_id_z 0
		.amdhsa_system_sgpr_workgroup_info 0
		.amdhsa_system_vgpr_workitem_id 2
		.amdhsa_next_free_vgpr 241
		.amdhsa_next_free_sgpr 102
		.amdhsa_accum_offset 244
		.amdhsa_reserve_vcc 1
		.amdhsa_float_round_mode_32 0
		.amdhsa_float_round_mode_16_64 0
		.amdhsa_float_denorm_mode_32 3
		.amdhsa_float_denorm_mode_16_64 3
		.amdhsa_dx10_clamp 1
		.amdhsa_ieee_mode 1
		.amdhsa_fp16_overflow 0
		.amdhsa_tg_split 0
		.amdhsa_exception_fp_ieee_invalid_op 0
		.amdhsa_exception_fp_denorm_src 0
		.amdhsa_exception_fp_ieee_div_zero 0
		.amdhsa_exception_fp_ieee_overflow 0
		.amdhsa_exception_fp_ieee_underflow 0
		.amdhsa_exception_fp_ieee_inexact 0
		.amdhsa_exception_int_div_zero 0
	.end_amdhsa_kernel

; __global__ __launch_bounds__(512, 2) void fwd_megakernel(Params p) {
amdhsa.kernels:
  - .agpr_count:     0
    .args:
      - .offset:         0
        .size:           168
        .value_kind:     by_value
      - .offset:         168
        .size:           4
        .value_kind:     hidden_block_count_x
      - .offset:         172
        .size:           4
        .value_kind:     hidden_block_count_y
      - .offset:         176
        .size:           4
        .value_kind:     hidden_block_count_z
      - .offset:         180
        .size:           2
        .value_kind:     hidden_group_size_x
      - .offset:         182
        .size:           2
        .value_kind:     hidden_group_size_y
      - .offset:         184
        .size:           2
        .value_kind:     hidden_group_size_z
      - .offset:         186
        .size:           2
        .value_kind:     hidden_remainder_x
      - .offset:         188
        .size:           2
        .value_kind:     hidden_remainder_y
      - .offset:         190
        .size:           2
        .value_kind:     hidden_remainder_z
      - .offset:         208
        .size:           8
        .value_kind:     hidden_global_offset_x
      - .offset:         216
        .size:           8
        .value_kind:     hidden_global_offset_y
      - .offset:         224
        .size:           8
        .value_kind:     hidden_global_offset_z
      - .offset:         232
        .size:           2
        .value_kind:     hidden_grid_dims
      - .offset:         256
        .size:           8
        .value_kind:     hidden_multigrid_sync_arg
      - .offset:         288
        .size:           4
        .value_kind:     hidden_dynamic_lds_size
    .group_segment_fixed_size: 16
    .kernarg_segment_align: 8
    .kernarg_segment_size: 424
    .language:       OpenCL C
    .language_version:
      - 2
      - 0
    .max_flat_workgroup_size: 512
    .name:           _Z14fwd_megakernel6Params
    .private_segment_fixed_size: 0
    .sgpr_count:     108
    .sgpr_spill_count: 9
    .symbol:         _Z14fwd_megakernel6Params.kd
    .uniform_work_group_size: 1
    .uses_dynamic_stack: false
    .vgpr_count:     241
    .vgpr_spill_count: 0
    .wavefront_size: 64
